# v7 + even-layer sample mixer: the two channel halves of the map/gate stage run on two workgroups (rk and rk+16) instead of one; each copy keeps only the instructions its half's stores depend on
# speedup vs baseline: 1.0144x; 1.0144x over previous
; __device__ __forceinline__ void sample_mix_even(Frame& F0, int j, int b) {
;     ...
;     for (int k = 0; k < 2; ++k) {
;         const int c = tid + 512 * k, g = c >> 8, win = 2 << g; const float xa = z[c];
;         const float* st = FIN(3) + ((size_t)(j * 128 + b) * 15) * 1024 + c;
;         float sr[15];
; #pragma unroll
;         for (int r = 0; r < 15; ++r) sr[r] = st[(size_t)r * 1024];
;         float s = xa;
; #pragma unroll
;         for (int r = 0; r < 15; ++r) s += (r >= 16 - win) ? sr[r] : 0.f;
;         pl[c] = s / (float)win - xa;
;         float* po = F.out + O_POOLS + ((size_t)(j * 128 + b) * 15) * 1024 + c;
; #pragma unroll
;         for (int r = 0; r < 14; ++r) po[(size_t)r * 1024] = sr[r + 1];
;         po[(size_t)14 * 1024] = xa;
;     }
;     __syncthreads();
.LBB0_1600:
	v_readlane_b32 s4, v254, 12
	v_readlane_b32 s20, v254, 37
	s_lshr_b32 s100, s93, 4
	s_and_b32 s93, s93, 15
	s_cmp_gt_i32 s93, 15
	v_readlane_b32 s5, v254, 13
	v_readlane_b32 s44, v254, 51
	v_readlane_b32 s21, v254, 38
	v_readlane_b32 s45, v254, 52
	s_cbranch_scc1 .LBB0_1610
	v_readlane_b32 s0, v254, 48
	s_lshl_b32 s18, s0, 4
	v_readlane_b32 s0, v254, 31
	s_add_i32 s19, s0, s18
	s_branch .LBB0_1603
.LBB0_1602:
	s_or_b64 exec, exec, s[4:5]
	v_cmp_lt_i32_e32 vcc, 14, v13
	s_waitcnt vmcnt(0)
	v_add_f32_e32 v28, v27, v28
	v_readlane_b32 s24, v254, 49
	v_cndmask_b32_e32 v0, 0, v31, vcc
	v_cmp_lt_i32_e32 vcc, 13, v13
	v_add_f32_e32 v0, v0, v28
	v_add_u32_e32 v54, s24, v26
	v_cndmask_b32_e32 v1, 0, v30, vcc
	v_cmp_lt_i32_e32 vcc, 12, v13
	v_add_f32_e32 v0, v1, v0
	v_ashrrev_i32_e32 v55, 31, v54
	v_cndmask_b32_e32 v14, 0, v29, vcc
	v_cmp_lt_i32_e32 vcc, 11, v13
	v_add_f32_e32 v0, v14, v0
	v_readlane_b32 s25, v254, 50
	v_cndmask_b32_e32 v15, 0, v8, vcc
	v_cmp_lt_i32_e32 vcc, 10, v13
	v_add_f32_e32 v0, v15, v0
	s_nop 0
	v_cndmask_b32_e32 v16, 0, v7, vcc
	v_cmp_lt_i32_e32 vcc, 9, v13
	v_add_f32_e32 v0, v16, v0
	s_nop 0
	v_cndmask_b32_e32 v17, 0, v6, vcc
	v_cmp_lt_i32_e32 vcc, 8, v13
	v_add_f32_e32 v0, v17, v0
	s_nop 0
	v_cndmask_b32_e32 v18, 0, v5, vcc
	v_cmp_lt_i32_e32 vcc, 7, v13
	v_add_f32_e32 v0, v18, v0
	s_nop 0
	v_cndmask_b32_e32 v19, 0, v4, vcc
	v_cmp_lt_i32_e32 vcc, 6, v13
	v_add_f32_e32 v0, v19, v0
	s_nop 0
	v_cndmask_b32_e32 v20, 0, v3, vcc
	v_cmp_lt_i32_e32 vcc, 5, v13
	v_add_f32_e32 v0, v20, v0
	s_nop 0
	v_cndmask_b32_e32 v21, 0, v2, vcc
	v_cmp_lt_i32_e32 vcc, 4, v13
	v_add_f32_e32 v0, v21, v0
	s_nop 0
	v_cndmask_b32_e32 v22, 0, v10, vcc
	v_cmp_lt_i32_e32 vcc, 3, v13
	v_add_f32_e32 v0, v22, v0
	s_nop 0
	v_cndmask_b32_e32 v23, 0, v9, vcc
	v_cmp_lt_i32_e32 vcc, 2, v13
	v_add_f32_e32 v0, v23, v0
	s_nop 0
	v_cndmask_b32_e32 v32, 0, v11, vcc
	v_cmp_lt_i32_e32 vcc, 1, v13
	v_cvt_f32_i32_e32 v13, v13
	v_add_f32_e32 v0, v32, v0
	v_cndmask_b32_e32 v34, 0, v12, vcc
	v_add_f32_e32 v14, v34, v0
	v_div_scale_f32 v15, s[4:5], v13, v13, v14
	v_rcp_f32_e32 v16, v15
	s_mov_b64 s[4:5], 0x4170000
	v_lshl_add_u64 v[0:1], v[24:25], 0, s[4:5]
	s_mov_b32 s4, 0x8000
	v_fma_f32 v17, -v15, v16, 1.0
	v_fmac_f32_e32 v16, v17, v16
	v_div_scale_f32 v17, vcc, v14, v13, v14
	v_mul_f32_e32 v18, v17, v16
	v_fma_f32 v19, -v15, v18, v17
	v_fmac_f32_e32 v18, v19, v16
	v_fma_f32 v15, -v15, v18, v17
	v_div_fmas_f32 v15, v15, v16, v18
	v_div_fixup_f32 v13, v15, v13, v14
	v_add_co_u32_e32 v14, vcc, s33, v0
	global_store_dword v[0:1], v31, off offset:2048
	s_nop 0
	v_addc_co_u32_e32 v15, vcc, 0, v1, vcc
	global_store_dword v[14:15], v30, off offset:2048
	v_add_co_u32_e32 v14, vcc, s70, v0
	v_sub_f32_e32 v13, v13, v27
	s_nop 0
	v_addc_co_u32_e32 v15, vcc, 0, v1, vcc
	global_store_dword v[14:15], v29, off offset:2048
	v_add_co_u32_e32 v14, vcc, s95, v0
	ds_write_b32 v33, v13 offset:2048
	s_nop 0
	v_addc_co_u32_e32 v15, vcc, 0, v1, vcc
	global_store_dword v[14:15], v8, off offset:2048
	v_add_co_u32_e32 v14, vcc, s94, v0
	s_nop 1
	v_addc_co_u32_e32 v15, vcc, 0, v1, vcc
	global_store_dword v[14:15], v7, off offset:2048
	v_add_co_u32_e32 v14, vcc, s81, v0
	s_nop 1
	v_addc_co_u32_e32 v15, vcc, 0, v1, vcc
	global_store_dword v[14:15], v6, off offset:2048
	v_add_co_u32_e32 v6, vcc, s71, v0
	s_nop 1
	v_addc_co_u32_e32 v7, vcc, 0, v1, vcc
	global_store_dword v[6:7], v5, off offset:2048
	v_add_co_u32_e32 v6, vcc, s82, v0
	s_nop 1
	v_addc_co_u32_e32 v7, vcc, 0, v1, vcc
	global_store_dword v[6:7], v4, off offset:2048
	v_add_co_u32_e32 v4, vcc, s4, v0
	s_mov_b32 s4, 0x9000
	s_nop 0
	v_addc_co_u32_e32 v5, vcc, 0, v1, vcc
	global_store_dword v[4:5], v3, off offset:2048
	v_add_co_u32_e32 v4, vcc, s4, v0
	s_mov_b32 s4, 0xa000
	s_nop 0
	v_addc_co_u32_e32 v5, vcc, 0, v1, vcc
	global_store_dword v[4:5], v2, off offset:2048
	v_add_co_u32_e32 v2, vcc, s4, v0
	s_mov_b32 s4, 0xb000
	s_nop 0
	v_addc_co_u32_e32 v3, vcc, 0, v1, vcc
	global_store_dword v[2:3], v10, off offset:2048
	v_add_co_u32_e32 v2, vcc, s4, v0
	s_mov_b32 s4, 0xc000
	s_nop 0
	v_addc_co_u32_e32 v3, vcc, 0, v1, vcc
	global_store_dword v[2:3], v9, off offset:2048
	v_add_co_u32_e32 v2, vcc, s4, v0
	s_mov_b32 s4, 0xd000
	s_nop 0
	v_addc_co_u32_e32 v3, vcc, 0, v1, vcc
	global_store_dword v[2:3], v11, off offset:2048
	v_add_co_u32_e32 v2, vcc, s4, v0
	s_mov_b32 s4, 0xe000
	s_nop 0
	v_addc_co_u32_e32 v3, vcc, 0, v1, vcc
	v_add_co_u32_e32 v0, vcc, s4, v0
	s_mov_b64 s[4:5], 0x6600000
	s_nop 0
	v_addc_co_u32_e32 v1, vcc, 0, v1, vcc
	global_store_dword v[0:1], v27, off offset:2048
	v_lshlrev_b32_e32 v0, 9, v48
	v_and_b32_e32 v200, 0x1fe00, v0
	v_lshl_add_u64 v[0:1], s[12:13], 0, v[200:201]
	v_lshl_add_u64 v[52:53], v[0:1], 0, s[4:5]
	v_lshlrev_b64 v[0:1], 17, v[54:55]
	v_lshl_add_u64 v[56:57], v[52:53], 0, v[0:1]
	global_store_dword v[2:3], v12, off offset:2048
	s_waitcnt lgkmcnt(0)
	s_barrier
	s_cmp_eq_u32 s100, 0
	s_cbranch_scc0 .Lsmx_hi
; #define LAS __attribute__((address_space(3)))
; __device__ __forceinline__ float dot4(f32x4 a, f32x4 b) { return (a[0] * b[0] + a[1] * b[1]) + (a[2] * b[2] + a[3] * b[3]); }
; __device__ __forceinline__ void unpack8(u32x4 w, f32x4& a, f32x4& b) { a = (f32x4){bflo(w.x), bfhi(w.x), bflo(w.y), bfhi(w.y)}; b = (f32x4){bflo(w.z), bfhi(w.z), bflo(w.w), bfhi(w.w)}; }
; __device__ __forceinline__ void sample_mix_even(Frame& F0, int j, int b) {
;     ...
;     __syncthreads();
;     float tot = 0.f;
; #pragma unroll
;     for (int i = 0; i < 8; ++i) tot += red[i];
;     const float rv = rsqrtf(tot * (1.0f / D) + EPS);
; #pragma unroll
;     for (int k = 0; k < 2; ++k) {
;         const int d = tid + 512 * k, g = d >> 8, dd = d & 255;
;         const bf16_t* pm = ((bf16_t*)(F.ws + WS_PMT)) + (size_t)(j * 4 + g) * 65536 + (size_t)dd * 256; const LAS float* pg = pl + g * 256;
;         float a = 0.f;
; #pragma unroll
;         for (int hb = 0; hb < 2; ++hb) {
;             u32x4 pr[16];
; #pragma unroll
;             for (int i = 0; i < 16; ++i) pr[i] = *(const u32x4*)(pm + hb * 128 + i * 8);
; #pragma unroll
;             for (int i = 0; i < 16; ++i) { f32x4 p0, p1; unpack8(pr[i], p0, p1); const LAS float* q = pg + hb * 128 + i * 8; a += dot4(p0, *(const LAS f32x4*)q) + dot4(p1, *(const LAS f32x4*)(q + 4)); }
	global_load_dwordx4 v[40:43], v[56:57], off
	global_load_dwordx4 v[44:47], v[56:57], off offset:16
	ds_read_b128 v[0:3], v201 offset:4096
	ds_read_b128 v[4:7], v201 offset:4112
	global_load_dwordx4 v[64:67], v[56:57], off offset:32
	global_load_dwordx4 v[68:71], v[56:57], off offset:48
	s_mov_b32 s4, 0x800000
	s_waitcnt lgkmcnt(1)
	v_add_f32_e32 v0, 0, v0
	v_add_f32_e32 v0, v0, v1
	v_add_f32_e32 v0, v0, v2
	v_add_f32_e32 v0, v0, v3
	s_waitcnt lgkmcnt(0)
	v_add_f32_e32 v0, v0, v4
	v_add_f32_e32 v0, v0, v5
	v_add_f32_e32 v0, v0, v6
	v_add_f32_e32 v0, v0, v7
	v_mov_b32_e32 v1, 0x358637bd
	v_fmamk_f32 v0, v0, 0x3a800000, v1
	v_cmp_gt_f32_e32 vcc, s4, v0
	v_mul_f32_e32 v1, 0x4b800000, v0
	s_load_dwordx8 s[4:11], s[14:15], 0x60
	v_cndmask_b32_e32 v0, v0, v1, vcc
	v_rsq_f32_e32 v0, v0
	s_lshl_b64 s[14:15], s[16:17], 12
	s_add_u32 s2, s2, s14
	s_addc_u32 s3, s3, s15
	v_mul_f32_e32 v1, 0x45800000, v0
	v_cndmask_b32_e32 v59, v0, v1, vcc
	v_and_b32_e32 v0, 0x3fffff00, v48
	v_lshl_add_u32 v63, v0, 2, 0
	global_load_dwordx4 v[32:35], v[56:57], off offset:112
	global_load_dwordx4 v[36:39], v[56:57], off offset:96
	global_load_dwordx4 v[72:75], v[56:57], off offset:80
	global_load_dwordx4 v[76:79], v[56:57], off offset:64
	global_load_dwordx4 v[16:19], v[56:57], off offset:176
	global_load_dwordx4 v[20:23], v[56:57], off offset:160
	global_load_dwordx4 v[24:27], v[56:57], off offset:144
	global_load_dwordx4 v[28:31], v[56:57], off offset:128
	global_load_dwordx4 v[0:3], v[56:57], off offset:240
	global_load_dwordx4 v[4:7], v[56:57], off offset:224
	global_load_dwordx4 v[8:11], v[56:57], off offset:208
	global_load_dwordx4 v[12:15], v[56:57], off offset:192
	ds_read_b128 v[80:83], v63
	s_lshl_b64 s[0:1], s[0:1], 12
	s_add_u32 s0, s12, s0
	s_addc_u32 s1, s13, s1
	s_add_i32 s93, s93, s22
	s_cmp_lt_i32 s93, 16
	s_waitcnt vmcnt(15)
	v_lshlrev_b32_e32 v92, 16, v40
	v_and_b32_e32 v93, 0xffff0000, v40
	v_lshlrev_b32_e32 v94, 16, v41
	v_and_b32_e32 v95, 0xffff0000, v41
	v_lshlrev_b32_e32 v96, 16, v42
	v_and_b32_e32 v97, 0xffff0000, v42
	v_lshlrev_b32_e32 v98, 16, v43
	v_and_b32_e32 v99, 0xffff0000, v43
	ds_read_b128 v[40:43], v63 offset:16
	ds_read_b128 v[84:87], v63 offset:32
	ds_read_b128 v[88:91], v63 offset:48
	s_waitcnt lgkmcnt(0)
	v_mul_f32_e32 v81, v81, v93
	v_fmac_f32_e32 v81, v80, v92
	v_mul_f32_e32 v41, v41, v97
	v_fmac_f32_e32 v41, v40, v96
	v_mul_f32_e32 v40, v43, v99
	v_mul_f32_e32 v80, v83, v95
	v_fmac_f32_e32 v40, v42, v98
	s_waitcnt vmcnt(14)
	v_and_b32_e32 v42, 0xffff0000, v44
	v_fmac_f32_e32 v80, v82, v94
	v_add_f32_e32 v40, v41, v40
	v_lshlrev_b32_e32 v41, 16, v44
	v_and_b32_e32 v44, 0xffff0000, v45
	v_mul_f32_e32 v42, v85, v42
	v_add_f32_e32 v80, v81, v80
	v_lshlrev_b32_e32 v43, 16, v45
	v_fmac_f32_e32 v42, v84, v41
	v_mul_f32_e32 v41, v87, v44
	v_add_f32_e32 v40, v80, v40
	v_lshlrev_b32_e32 v45, 16, v46
	v_and_b32_e32 v46, 0xffff0000, v46
	v_lshlrev_b32_e32 v80, 16, v47
	v_and_b32_e32 v47, 0xffff0000, v47
	v_fmac_f32_e32 v41, v86, v43
	v_add_f32_e32 v41, v42, v41
	v_mul_f32_e32 v42, v89, v46
	v_mul_f32_e32 v43, v91, v47
	v_fmac_f32_e32 v42, v88, v45
	v_fmac_f32_e32 v43, v90, v80
	v_add_f32_e32 v42, v42, v43
	v_add_f32_e32 v40, 0, v40
	v_add_f32_e32 v41, v41, v42
	v_add_f32_e32 v80, v40, v41
	ds_read_b128 v[40:43], v63 offset:64
	s_waitcnt vmcnt(13)
	v_and_b32_e32 v44, 0xffff0000, v64
	v_lshlrev_b32_e32 v81, 16, v64
	v_lshlrev_b32_e32 v64, 16, v65
	v_and_b32_e32 v65, 0xffff0000, v65
	s_waitcnt lgkmcnt(0)
	v_mul_f32_e32 v41, v41, v44
	ds_read_b128 v[44:47], v63 offset:80
	v_fmac_f32_e32 v41, v40, v81
	v_mul_f32_e32 v40, v43, v65
	v_lshlrev_b32_e32 v82, 16, v66
	v_and_b32_e32 v66, 0xffff0000, v66
	v_lshlrev_b32_e32 v83, 16, v67
	v_and_b32_e32 v67, 0xffff0000, v67
	v_fmac_f32_e32 v40, v42, v64
	v_add_f32_e32 v40, v41, v40
	s_waitcnt lgkmcnt(0)
	v_mul_f32_e32 v41, v45, v66
	v_mul_f32_e32 v42, v47, v67
	v_fmac_f32_e32 v41, v44, v82
	v_fmac_f32_e32 v42, v46, v83
	v_add_f32_e32 v41, v41, v42
	v_add_f32_e32 v40, v40, v41
	v_add_f32_e32 v64, v80, v40
	ds_read_b128 v[40:43], v63 offset:96
	s_waitcnt vmcnt(12)
	v_and_b32_e32 v44, 0xffff0000, v68
	v_lshlrev_b32_e32 v65, 16, v68
	v_and_b32_e32 v67, 0xffff0000, v69
	v_lshlrev_b32_e32 v66, 16, v69
	s_waitcnt lgkmcnt(0)
	v_mul_f32_e32 v41, v41, v44
	ds_read_b128 v[44:47], v63 offset:112
	v_fmac_f32_e32 v41, v40, v65
	v_mul_f32_e32 v40, v43, v67
	v_lshlrev_b32_e32 v68, 16, v70
	v_and_b32_e32 v69, 0xffff0000, v70
	v_lshlrev_b32_e32 v70, 16, v71
	v_and_b32_e32 v71, 0xffff0000, v71
	v_fmac_f32_e32 v40, v42, v66
	v_add_f32_e32 v40, v41, v40
	s_waitcnt lgkmcnt(0)
	v_mul_f32_e32 v41, v45, v69
	v_mul_f32_e32 v42, v47, v71
	v_fmac_f32_e32 v41, v44, v68
	v_fmac_f32_e32 v42, v46, v70
	v_add_f32_e32 v41, v41, v42
	v_add_f32_e32 v40, v40, v41
	v_add_f32_e32 v64, v64, v40
	ds_read_b128 v[40:43], v63 offset:128
	s_waitcnt vmcnt(8)
	v_and_b32_e32 v44, 0xffff0000, v76
	v_lshlrev_b32_e32 v65, 16, v76
	v_and_b32_e32 v67, 0xffff0000, v77
	v_lshlrev_b32_e32 v66, 16, v77
	s_waitcnt lgkmcnt(0)
	v_mul_f32_e32 v41, v41, v44
	ds_read_b128 v[44:47], v63 offset:144
	v_fmac_f32_e32 v41, v40, v65
	v_mul_f32_e32 v40, v43, v67
	v_and_b32_e32 v69, 0xffff0000, v78
	v_and_b32_e32 v71, 0xffff0000, v79
	v_fmac_f32_e32 v40, v42, v66
	v_lshlrev_b32_e32 v68, 16, v78
	v_lshlrev_b32_e32 v70, 16, v79
	v_add_f32_e32 v40, v41, v40
	s_waitcnt lgkmcnt(0)
	v_mul_f32_e32 v41, v45, v69
	v_mul_f32_e32 v42, v47, v71
	v_fmac_f32_e32 v41, v44, v68
	v_fmac_f32_e32 v42, v46, v70
	v_add_f32_e32 v41, v41, v42
	v_add_f32_e32 v40, v40, v41
	v_add_f32_e32 v64, v64, v40
	ds_read_b128 v[40:43], v63 offset:160
	v_and_b32_e32 v44, 0xffff0000, v72
	v_lshlrev_b32_e32 v65, 16, v72
	v_and_b32_e32 v67, 0xffff0000, v73
	v_lshlrev_b32_e32 v66, 16, v73
	s_waitcnt lgkmcnt(0)
; #define LAS __attribute__((address_space(3)))
; __device__ __forceinline__ float dot4(f32x4 a, f32x4 b) { return (a[0] * b[0] + a[1] * b[1]) + (a[2] * b[2] + a[3] * b[3]); }
; __device__ __forceinline__ void unpack8(u32x4 w, f32x4& a, f32x4& b) { a = (f32x4){bflo(w.x), bfhi(w.x), bflo(w.y), bfhi(w.y)}; b = (f32x4){bflo(w.z), bfhi(w.z), bflo(w.w), bfhi(w.w)}; }
; __device__ __forceinline__ void sample_mix_even(Frame& F0, int j, int b) {
;     ...
;         const bf16_t* pm = ((bf16_t*)(F.ws + WS_PMT)) + (size_t)(j * 4 + g) * 65536 + (size_t)dd * 256; const LAS float* pg = pl + g * 256;
;         float a = 0.f;
; #pragma unroll
;         for (int hb = 0; hb < 2; ++hb) {
;             u32x4 pr[16];
; #pragma unroll
;             for (int i = 0; i < 16; ++i) pr[i] = *(const u32x4*)(pm + hb * 128 + i * 8);
; #pragma unroll
;             for (int i = 0; i < 16; ++i) { f32x4 p0, p1; unpack8(pr[i], p0, p1); const LAS float* q = pg + hb * 128 + i * 8; a += dot4(p0, *(const LAS f32x4*)q) + dot4(p1, *(const LAS f32x4*)(q + 4)); }
	v_mul_f32_e32 v41, v41, v44
	ds_read_b128 v[44:47], v63 offset:176
	v_fmac_f32_e32 v41, v40, v65
	v_mul_f32_e32 v40, v43, v67
	v_and_b32_e32 v69, 0xffff0000, v74
	v_and_b32_e32 v71, 0xffff0000, v75
	v_fmac_f32_e32 v40, v42, v66
	v_lshlrev_b32_e32 v68, 16, v74
	v_lshlrev_b32_e32 v70, 16, v75
	v_add_f32_e32 v40, v41, v40
	s_waitcnt lgkmcnt(0)
	v_mul_f32_e32 v41, v45, v69
	v_mul_f32_e32 v42, v47, v71
	v_fmac_f32_e32 v41, v44, v68
	v_fmac_f32_e32 v42, v46, v70
	v_add_f32_e32 v41, v41, v42
	v_add_f32_e32 v40, v40, v41
	v_add_f32_e32 v44, v64, v40
	ds_read_b128 v[40:43], v63 offset:192
	v_lshlrev_b32_e32 v45, 16, v36
	v_and_b32_e32 v36, 0xffff0000, v36
	v_lshlrev_b32_e32 v46, 16, v37
	v_and_b32_e32 v47, 0xffff0000, v37
	v_lshlrev_b32_e32 v64, 16, v38
	v_and_b32_e32 v65, 0xffff0000, v38
	v_lshlrev_b32_e32 v66, 16, v39
	v_and_b32_e32 v67, 0xffff0000, v39
	s_waitcnt lgkmcnt(0)
	v_mul_f32_e32 v41, v41, v36
	ds_read_b128 v[36:39], v63 offset:208
	v_fmac_f32_e32 v41, v40, v45
	v_mul_f32_e32 v40, v43, v47
	v_fmac_f32_e32 v40, v42, v46
	v_add_f32_e32 v40, v41, v40
	s_waitcnt lgkmcnt(0)
	v_mul_f32_e32 v37, v37, v65
	v_fmac_f32_e32 v37, v36, v64
	v_mul_f32_e32 v36, v39, v67
	v_fmac_f32_e32 v36, v38, v66
	v_add_f32_e32 v36, v37, v36
	v_add_f32_e32 v36, v40, v36
	v_add_f32_e32 v40, v44, v36
	ds_read_b128 v[36:39], v63 offset:224
	v_lshlrev_b32_e32 v41, 16, v32
	v_and_b32_e32 v32, 0xffff0000, v32
	v_lshlrev_b32_e32 v42, 16, v33
	v_and_b32_e32 v43, 0xffff0000, v33
	v_lshlrev_b32_e32 v44, 16, v34
	v_and_b32_e32 v45, 0xffff0000, v34
	v_lshlrev_b32_e32 v46, 16, v35
	v_and_b32_e32 v47, 0xffff0000, v35
	s_waitcnt lgkmcnt(0)
	v_mul_f32_e32 v37, v37, v32
	ds_read_b128 v[32:35], v63 offset:240
	v_fmac_f32_e32 v37, v36, v41
	v_mul_f32_e32 v36, v39, v43
	v_fmac_f32_e32 v36, v38, v42
	v_add_f32_e32 v36, v37, v36
	s_waitcnt lgkmcnt(0)
	v_mul_f32_e32 v33, v33, v45
	v_fmac_f32_e32 v33, v32, v44
	v_mul_f32_e32 v32, v35, v47
	v_fmac_f32_e32 v32, v34, v46
	v_add_f32_e32 v32, v33, v32
	v_add_f32_e32 v32, v36, v32
	v_add_f32_e32 v36, v40, v32
	ds_read_b128 v[32:35], v63 offset:256
	s_waitcnt vmcnt(4)
	v_lshlrev_b32_e32 v37, 16, v28
	v_and_b32_e32 v28, 0xffff0000, v28
	v_lshlrev_b32_e32 v38, 16, v29
	v_and_b32_e32 v39, 0xffff0000, v29
	v_lshlrev_b32_e32 v40, 16, v30
	v_and_b32_e32 v41, 0xffff0000, v30
	v_lshlrev_b32_e32 v42, 16, v31
	v_and_b32_e32 v43, 0xffff0000, v31
	s_waitcnt lgkmcnt(0)
	v_mul_f32_e32 v33, v33, v28
	ds_read_b128 v[28:31], v63 offset:272
	v_fmac_f32_e32 v33, v32, v37
	v_mul_f32_e32 v32, v35, v39
	v_fmac_f32_e32 v32, v34, v38
	v_add_f32_e32 v32, v33, v32
	s_waitcnt lgkmcnt(0)
	v_mul_f32_e32 v29, v29, v41
	v_fmac_f32_e32 v29, v28, v40
	v_mul_f32_e32 v28, v31, v43
	v_fmac_f32_e32 v28, v30, v42
	v_add_f32_e32 v28, v29, v28
	v_add_f32_e32 v28, v32, v28
	v_add_f32_e32 v32, v36, v28
	ds_read_b128 v[28:31], v63 offset:288
	v_lshlrev_b32_e32 v33, 16, v24
	v_and_b32_e32 v24, 0xffff0000, v24
	v_lshlrev_b32_e32 v34, 16, v25
	v_and_b32_e32 v35, 0xffff0000, v25
	v_lshlrev_b32_e32 v36, 16, v26
	v_and_b32_e32 v37, 0xffff0000, v26
	v_lshlrev_b32_e32 v38, 16, v27
	v_and_b32_e32 v39, 0xffff0000, v27
	s_waitcnt lgkmcnt(0)
	v_mul_f32_e32 v29, v29, v24
	ds_read_b128 v[24:27], v63 offset:304
	v_fmac_f32_e32 v29, v28, v33
	v_mul_f32_e32 v28, v31, v35
	v_fmac_f32_e32 v28, v30, v34
	v_add_f32_e32 v28, v29, v28
	s_waitcnt lgkmcnt(0)
	v_mul_f32_e32 v25, v25, v37
	v_fmac_f32_e32 v25, v24, v36
	v_mul_f32_e32 v24, v27, v39
	v_fmac_f32_e32 v24, v26, v38
	v_add_f32_e32 v24, v25, v24
	v_add_f32_e32 v24, v28, v24
	v_add_f32_e32 v28, v32, v24
	ds_read_b128 v[24:27], v63 offset:320
	v_lshlrev_b32_e32 v29, 16, v20
	v_and_b32_e32 v20, 0xffff0000, v20
	v_lshlrev_b32_e32 v30, 16, v21
	v_and_b32_e32 v31, 0xffff0000, v21
	v_lshlrev_b32_e32 v32, 16, v22
	v_and_b32_e32 v33, 0xffff0000, v22
	v_lshlrev_b32_e32 v34, 16, v23
	v_and_b32_e32 v35, 0xffff0000, v23
	s_waitcnt lgkmcnt(0)
	v_mul_f32_e32 v25, v25, v20
	ds_read_b128 v[20:23], v63 offset:336
	v_fmac_f32_e32 v25, v24, v29
	v_mul_f32_e32 v24, v27, v31
	v_fmac_f32_e32 v24, v26, v30
	v_add_f32_e32 v24, v25, v24
	s_waitcnt lgkmcnt(0)
	v_mul_f32_e32 v21, v21, v33
	v_fmac_f32_e32 v21, v20, v32
	v_mul_f32_e32 v20, v23, v35
	v_fmac_f32_e32 v20, v22, v34
	v_add_f32_e32 v20, v21, v20
	v_add_f32_e32 v20, v24, v20
	v_add_f32_e32 v24, v28, v20
	ds_read_b128 v[20:23], v63 offset:352
	v_lshlrev_b32_e32 v25, 16, v16
	v_and_b32_e32 v16, 0xffff0000, v16
	v_lshlrev_b32_e32 v26, 16, v17
	v_and_b32_e32 v27, 0xffff0000, v17
	v_lshlrev_b32_e32 v28, 16, v18
	v_and_b32_e32 v29, 0xffff0000, v18
	v_lshlrev_b32_e32 v30, 16, v19
	v_and_b32_e32 v31, 0xffff0000, v19
	s_waitcnt lgkmcnt(0)
	v_mul_f32_e32 v21, v21, v16
	ds_read_b128 v[16:19], v63 offset:368
	v_fmac_f32_e32 v21, v20, v25
	v_mul_f32_e32 v20, v23, v27
	v_fmac_f32_e32 v20, v22, v26
	v_add_f32_e32 v20, v21, v20
	s_waitcnt lgkmcnt(0)
	v_mul_f32_e32 v17, v17, v29
	v_fmac_f32_e32 v17, v16, v28
	v_mul_f32_e32 v16, v19, v31
	v_fmac_f32_e32 v16, v18, v30
	v_add_f32_e32 v16, v17, v16
	v_add_f32_e32 v16, v20, v16
	global_load_dwordx4 v[64:67], v[56:57], off offset:256
	v_add_f32_e32 v20, v24, v16
	ds_read_b128 v[16:19], v63 offset:384
	s_waitcnt vmcnt(1)
	v_lshlrev_b32_e32 v21, 16, v12
	v_and_b32_e32 v12, 0xffff0000, v12
	v_lshlrev_b32_e32 v22, 16, v13
	v_and_b32_e32 v23, 0xffff0000, v13
	v_lshlrev_b32_e32 v24, 16, v14
	v_and_b32_e32 v25, 0xffff0000, v14
	v_lshlrev_b32_e32 v26, 16, v15
	v_and_b32_e32 v27, 0xffff0000, v15
	s_waitcnt lgkmcnt(0)
	v_mul_f32_e32 v17, v17, v12
	ds_read_b128 v[12:15], v63 offset:400
	v_fmac_f32_e32 v17, v16, v21
	v_mul_f32_e32 v16, v19, v23
	global_load_dwordx4 v[68:71], v[56:57], off offset:272
	v_fmac_f32_e32 v16, v18, v22
	s_waitcnt lgkmcnt(0)
; #define LAS __attribute__((address_space(3)))
; __device__ __forceinline__ float dot4(f32x4 a, f32x4 b) { return (a[0] * b[0] + a[1] * b[1]) + (a[2] * b[2] + a[3] * b[3]); }
; __device__ __forceinline__ void unpack8(u32x4 w, f32x4& a, f32x4& b) { a = (f32x4){bflo(w.x), bfhi(w.x), bflo(w.y), bfhi(w.y)}; b = (f32x4){bflo(w.z), bfhi(w.z), bflo(w.w), bfhi(w.w)}; }
; __device__ __forceinline__ void sample_mix_even(Frame& F0, int j, int b) {
;     ...
;         const bf16_t* pm = ((bf16_t*)(F.ws + WS_PMT)) + (size_t)(j * 4 + g) * 65536 + (size_t)dd * 256; const LAS float* pg = pl + g * 256;
;         float a = 0.f;
; #pragma unroll
;         for (int hb = 0; hb < 2; ++hb) {
;             u32x4 pr[16];
; #pragma unroll
;             for (int i = 0; i < 16; ++i) pr[i] = *(const u32x4*)(pm + hb * 128 + i * 8);
; #pragma unroll
;             for (int i = 0; i < 16; ++i) { f32x4 p0, p1; unpack8(pr[i], p0, p1); const LAS float* q = pg + hb * 128 + i * 8; a += dot4(p0, *(const LAS f32x4*)q) + dot4(p1, *(const LAS f32x4*)(q + 4)); }
	v_mul_f32_e32 v13, v13, v25
	v_fmac_f32_e32 v13, v12, v24
	v_mul_f32_e32 v12, v15, v27
	v_fmac_f32_e32 v12, v14, v26
	v_add_f32_e32 v16, v17, v16
	v_add_f32_e32 v12, v13, v12
	v_add_f32_e32 v12, v16, v12
	v_add_f32_e32 v16, v20, v12
	ds_read_b128 v[12:15], v63 offset:416
	v_lshlrev_b32_e32 v17, 16, v8
	v_and_b32_e32 v8, 0xffff0000, v8
	v_lshlrev_b32_e32 v18, 16, v9
	v_and_b32_e32 v19, 0xffff0000, v9
	v_lshlrev_b32_e32 v20, 16, v10
	v_and_b32_e32 v21, 0xffff0000, v10
	v_lshlrev_b32_e32 v22, 16, v11
	v_and_b32_e32 v23, 0xffff0000, v11
	s_waitcnt lgkmcnt(0)
	v_mul_f32_e32 v13, v13, v8
	ds_read_b128 v[8:11], v63 offset:432
	global_load_dwordx4 v[72:75], v[56:57], off offset:288
	v_fmac_f32_e32 v13, v12, v17
	v_mul_f32_e32 v12, v15, v19
	v_fmac_f32_e32 v12, v14, v18
	s_waitcnt lgkmcnt(0)
	v_mul_f32_e32 v9, v9, v21
	v_fmac_f32_e32 v9, v8, v20
	v_mul_f32_e32 v8, v11, v23
	v_fmac_f32_e32 v8, v10, v22
	v_add_f32_e32 v12, v13, v12
	v_add_f32_e32 v8, v9, v8
	v_add_f32_e32 v8, v12, v8
	v_add_f32_e32 v12, v16, v8
	ds_read_b128 v[8:11], v63 offset:448
	v_lshlrev_b32_e32 v13, 16, v4
	v_and_b32_e32 v4, 0xffff0000, v4
	v_lshlrev_b32_e32 v14, 16, v5
	v_and_b32_e32 v15, 0xffff0000, v5
	v_lshlrev_b32_e32 v16, 16, v6
	v_and_b32_e32 v17, 0xffff0000, v6
	v_lshlrev_b32_e32 v18, 16, v7
	v_and_b32_e32 v19, 0xffff0000, v7
	s_waitcnt lgkmcnt(0)
	v_mul_f32_e32 v9, v9, v4
	ds_read_b128 v[4:7], v63 offset:464
	global_load_dwordx4 v[44:47], v[56:57], off offset:304
	v_fmac_f32_e32 v9, v8, v13
	v_mul_f32_e32 v8, v11, v15
	v_fmac_f32_e32 v8, v10, v14
	s_waitcnt lgkmcnt(0)
	v_mul_f32_e32 v5, v5, v17
	v_fmac_f32_e32 v5, v4, v16
	v_mul_f32_e32 v4, v7, v19
	v_fmac_f32_e32 v4, v6, v18
	v_add_f32_e32 v8, v9, v8
	v_add_f32_e32 v4, v5, v4
	v_add_f32_e32 v4, v8, v4
	v_add_f32_e32 v8, v12, v4
	ds_read_b128 v[4:7], v63 offset:480
	v_lshlrev_b32_e32 v9, 16, v0
	v_and_b32_e32 v0, 0xffff0000, v0
	v_lshlrev_b32_e32 v10, 16, v1
	v_and_b32_e32 v11, 0xffff0000, v1
	v_lshlrev_b32_e32 v12, 16, v2
	v_and_b32_e32 v13, 0xffff0000, v2
	v_lshlrev_b32_e32 v14, 16, v3
	v_and_b32_e32 v15, 0xffff0000, v3
	s_waitcnt lgkmcnt(0)
	v_mul_f32_e32 v5, v5, v0
	ds_read_b128 v[0:3], v63 offset:496
	v_fmac_f32_e32 v5, v4, v9
	v_mul_f32_e32 v4, v7, v11
	v_fmac_f32_e32 v4, v6, v10
	v_add_f32_e32 v4, v5, v4
	s_waitcnt lgkmcnt(0)
	v_mul_f32_e32 v1, v1, v13
	v_fmac_f32_e32 v1, v0, v12
	v_mul_f32_e32 v0, v3, v15
	v_fmac_f32_e32 v0, v2, v14
	v_add_f32_e32 v0, v1, v0
	v_add_f32_e32 v0, v4, v0
	v_add_f32_e32 v84, v8, v0
	global_load_dwordx4 v[32:35], v[56:57], off offset:368
	global_load_dwordx4 v[36:39], v[56:57], off offset:352
	global_load_dwordx4 v[40:43], v[56:57], off offset:336
	global_load_dwordx4 v[76:79], v[56:57], off offset:320
	global_load_dwordx4 v[16:19], v[56:57], off offset:432
	global_load_dwordx4 v[20:23], v[56:57], off offset:416
	global_load_dwordx4 v[24:27], v[56:57], off offset:400
	global_load_dwordx4 v[28:31], v[56:57], off offset:384
	global_load_dwordx4 v[0:3], v[56:57], off offset:496
	global_load_dwordx4 v[4:7], v[56:57], off offset:480
	global_load_dwordx4 v[8:11], v[56:57], off offset:464
	global_load_dwordx4 v[12:15], v[56:57], off offset:448
	ds_read_b128 v[80:83], v63 offset:512
	s_waitcnt vmcnt(15)
	v_lshlrev_b32_e32 v56, 16, v64
	v_and_b32_e32 v57, 0xffff0000, v64
	v_lshlrev_b32_e32 v85, 16, v65
	v_and_b32_e32 v86, 0xffff0000, v65
	v_lshlrev_b32_e32 v87, 16, v66
	v_and_b32_e32 v88, 0xffff0000, v66
	v_lshlrev_b32_e32 v89, 16, v67
	v_and_b32_e32 v90, 0xffff0000, v67
	ds_read_b128 v[64:67], v63 offset:528
	s_waitcnt lgkmcnt(1)
	v_mul_f32_e32 v57, v81, v57
	v_fmac_f32_e32 v57, v80, v56
	v_mul_f32_e32 v56, v83, v86
	v_fmac_f32_e32 v56, v82, v85
	v_add_f32_e32 v56, v57, v56
	s_waitcnt lgkmcnt(0)
	v_mul_f32_e32 v57, v65, v88
	v_fmac_f32_e32 v57, v64, v87
	v_mul_f32_e32 v64, v67, v90
	v_fmac_f32_e32 v64, v66, v89
	v_add_f32_e32 v57, v57, v64
	ds_read_b128 v[64:67], v63 offset:544
	v_add_f32_e32 v56, v56, v57
	s_waitcnt vmcnt(14)
	v_lshlrev_b32_e32 v57, 16, v68
	v_and_b32_e32 v68, 0xffff0000, v68
	v_add_f32_e32 v56, v84, v56
	v_lshlrev_b32_e32 v80, 16, v69
	v_and_b32_e32 v81, 0xffff0000, v69
	v_lshlrev_b32_e32 v82, 16, v70
	v_and_b32_e32 v83, 0xffff0000, v70
	v_lshlrev_b32_e32 v84, 16, v71
	v_and_b32_e32 v85, 0xffff0000, v71
	s_waitcnt lgkmcnt(0)
	v_mul_f32_e32 v65, v65, v68
	ds_read_b128 v[68:71], v63 offset:560
	v_fmac_f32_e32 v65, v64, v57
	v_mul_f32_e32 v57, v67, v81
	v_fmac_f32_e32 v57, v66, v80
	v_add_f32_e32 v57, v65, v57
	s_waitcnt lgkmcnt(0)
	v_mul_f32_e32 v64, v69, v83
	v_mul_f32_e32 v65, v71, v85
	v_fmac_f32_e32 v64, v68, v82
	v_fmac_f32_e32 v65, v70, v84
	v_add_f32_e32 v64, v64, v65
	v_add_f32_e32 v57, v57, v64
	ds_read_b128 v[64:67], v63 offset:576
	s_waitcnt vmcnt(13)
	v_and_b32_e32 v68, 0xffff0000, v72
	v_add_f32_e32 v56, v56, v57
	v_lshlrev_b32_e32 v57, 16, v72
	v_lshlrev_b32_e32 v72, 16, v73
	s_waitcnt lgkmcnt(0)
	v_mul_f32_e32 v65, v65, v68
	ds_read_b128 v[68:71], v63 offset:592
	v_and_b32_e32 v73, 0xffff0000, v73
	v_fmac_f32_e32 v65, v64, v57
	v_mul_f32_e32 v57, v67, v73
	v_lshlrev_b32_e32 v80, 16, v74
	v_and_b32_e32 v74, 0xffff0000, v74
	v_lshlrev_b32_e32 v81, 16, v75
	v_and_b32_e32 v75, 0xffff0000, v75
	v_fmac_f32_e32 v57, v66, v72
	v_add_f32_e32 v57, v65, v57
	s_waitcnt lgkmcnt(0)
	v_mul_f32_e32 v64, v69, v74
	v_mul_f32_e32 v65, v71, v75
	v_fmac_f32_e32 v64, v68, v80
	v_fmac_f32_e32 v65, v70, v81
	v_add_f32_e32 v64, v64, v65
	v_add_f32_e32 v57, v57, v64
	ds_read_b128 v[64:67], v63 offset:608
	v_add_f32_e32 v56, v56, v57
	s_waitcnt vmcnt(12)
; #define LAS __attribute__((address_space(3)))
; __device__ __forceinline__ float silu_f(float x) { return x * __builtin_amdgcn_rcpf(1.f + __builtin_amdgcn_exp2f(-1.4426950408889634f * x)); }
; __device__ __forceinline__ float dot4(f32x4 a, f32x4 b) { return (a[0] * b[0] + a[1] * b[1]) + (a[2] * b[2] + a[3] * b[3]); }
; __device__ __forceinline__ void unpack8(u32x4 w, f32x4& a, f32x4& b) { a = (f32x4){bflo(w.x), bfhi(w.x), bflo(w.y), bfhi(w.y)}; b = (f32x4){bflo(w.z), bfhi(w.z), bflo(w.w), bfhi(w.w)}; }
; __device__ __forceinline__ void sample_mix_even(Frame& F0, int j, int b) {
;     ...
;         const bf16_t* pm = ((bf16_t*)(F.ws + WS_PMT)) + (size_t)(j * 4 + g) * 65536 + (size_t)dd * 256; const LAS float* pg = pl + g * 256;
;         float a = 0.f;
; #pragma unroll
;         for (int hb = 0; hb < 2; ++hb) {
;             u32x4 pr[16];
; #pragma unroll
;             for (int i = 0; i < 16; ++i) pr[i] = *(const u32x4*)(pm + hb * 128 + i * 8);
; #pragma unroll
;             for (int i = 0; i < 16; ++i) { f32x4 p0, p1; unpack8(pr[i], p0, p1); const LAS float* q = pg + hb * 128 + i * 8; a += dot4(p0, *(const LAS f32x4*)q) + dot4(p1, *(const LAS f32x4*)(q + 4)); }
;         }
;         const float ya = a * FIN(12)[j * 1024 + d] * silu_f(z[1024 + d]);
;         const float vn = vv[k] * rv * FIN(15)[j * 1024 + d];
	v_lshlrev_b32_e32 v57, 16, v44
	v_and_b32_e32 v44, 0xffff0000, v44
	v_lshlrev_b32_e32 v68, 16, v45
	v_and_b32_e32 v69, 0xffff0000, v45
	v_lshlrev_b32_e32 v70, 16, v46
	v_and_b32_e32 v71, 0xffff0000, v46
	v_lshlrev_b32_e32 v72, 16, v47
	v_and_b32_e32 v73, 0xffff0000, v47
	s_waitcnt lgkmcnt(0)
	v_mul_f32_e32 v65, v65, v44
	ds_read_b128 v[44:47], v63 offset:624
	v_fmac_f32_e32 v65, v64, v57
	v_mul_f32_e32 v57, v67, v69
	v_fmac_f32_e32 v57, v66, v68
	v_add_f32_e32 v57, v65, v57
	s_waitcnt lgkmcnt(0)
	v_mul_f32_e32 v45, v45, v71
	v_fmac_f32_e32 v45, v44, v70
	v_mul_f32_e32 v44, v47, v73
	v_fmac_f32_e32 v44, v46, v72
	v_add_f32_e32 v44, v45, v44
	v_add_f32_e32 v44, v57, v44
	v_add_f32_e32 v56, v56, v44
	ds_read_b128 v[44:47], v63 offset:640
	s_waitcnt vmcnt(8)
	v_and_b32_e32 v64, 0xffff0000, v76
	v_lshlrev_b32_e32 v57, 16, v76
	v_and_b32_e32 v69, 0xffff0000, v77
	v_lshlrev_b32_e32 v68, 16, v77
	s_waitcnt lgkmcnt(0)
	v_mul_f32_e32 v45, v45, v64
	ds_read_b128 v[64:67], v63 offset:656
	v_fmac_f32_e32 v45, v44, v57
	v_mul_f32_e32 v44, v47, v69
	v_and_b32_e32 v71, 0xffff0000, v78
	v_and_b32_e32 v73, 0xffff0000, v79
	v_fmac_f32_e32 v44, v46, v68
	v_lshlrev_b32_e32 v70, 16, v78
	v_lshlrev_b32_e32 v72, 16, v79
	v_add_f32_e32 v44, v45, v44
	s_waitcnt lgkmcnt(0)
	v_mul_f32_e32 v45, v65, v71
	v_mul_f32_e32 v46, v67, v73
	v_fmac_f32_e32 v45, v64, v70
	v_fmac_f32_e32 v46, v66, v72
	v_add_f32_e32 v45, v45, v46
	v_add_f32_e32 v44, v44, v45
	v_add_f32_e32 v56, v56, v44
	ds_read_b128 v[44:47], v63 offset:672
	v_lshlrev_b32_e32 v57, 16, v40
	v_and_b32_e32 v40, 0xffff0000, v40
	v_lshlrev_b32_e32 v64, 16, v41
	v_and_b32_e32 v65, 0xffff0000, v41
	v_lshlrev_b32_e32 v66, 16, v42
	v_and_b32_e32 v67, 0xffff0000, v42
	v_lshlrev_b32_e32 v68, 16, v43
	v_and_b32_e32 v69, 0xffff0000, v43
	s_waitcnt lgkmcnt(0)
	v_mul_f32_e32 v45, v45, v40
	ds_read_b128 v[40:43], v63 offset:688
	v_fmac_f32_e32 v45, v44, v57
	v_mul_f32_e32 v44, v47, v65
	v_fmac_f32_e32 v44, v46, v64
	v_add_f32_e32 v44, v45, v44
	s_waitcnt lgkmcnt(0)
	v_mul_f32_e32 v41, v41, v67
	v_fmac_f32_e32 v41, v40, v66
	v_mul_f32_e32 v40, v43, v69
	v_fmac_f32_e32 v40, v42, v68
	v_add_f32_e32 v40, v41, v40
	v_add_f32_e32 v40, v44, v40
	v_add_f32_e32 v44, v56, v40
	ds_read_b128 v[40:43], v63 offset:704
	v_lshlrev_b32_e32 v45, 16, v36
	v_and_b32_e32 v36, 0xffff0000, v36
	v_lshlrev_b32_e32 v46, 16, v37
	v_and_b32_e32 v47, 0xffff0000, v37
	v_lshlrev_b32_e32 v56, 16, v38
	v_and_b32_e32 v57, 0xffff0000, v38
	v_lshlrev_b32_e32 v64, 16, v39
	v_and_b32_e32 v65, 0xffff0000, v39
	s_waitcnt lgkmcnt(0)
	v_mul_f32_e32 v41, v41, v36
	ds_read_b128 v[36:39], v63 offset:720
	v_fmac_f32_e32 v41, v40, v45
	v_mul_f32_e32 v40, v43, v47
	v_fmac_f32_e32 v40, v42, v46
	v_add_f32_e32 v40, v41, v40
	s_waitcnt lgkmcnt(0)
	v_mul_f32_e32 v37, v37, v57
	v_fmac_f32_e32 v37, v36, v56
	v_mul_f32_e32 v36, v39, v65
	v_fmac_f32_e32 v36, v38, v64
	v_add_f32_e32 v36, v37, v36
	v_add_f32_e32 v36, v40, v36
	v_add_f32_e32 v40, v44, v36
	ds_read_b128 v[36:39], v63 offset:736
	v_lshlrev_b32_e32 v41, 16, v32
	v_and_b32_e32 v32, 0xffff0000, v32
	v_lshlrev_b32_e32 v42, 16, v33
	v_and_b32_e32 v43, 0xffff0000, v33
	v_lshlrev_b32_e32 v44, 16, v34
	v_and_b32_e32 v45, 0xffff0000, v34
	v_lshlrev_b32_e32 v46, 16, v35
	v_and_b32_e32 v47, 0xffff0000, v35
	s_waitcnt lgkmcnt(0)
	v_mul_f32_e32 v37, v37, v32
	ds_read_b128 v[32:35], v63 offset:752
	v_fmac_f32_e32 v37, v36, v41
	v_mul_f32_e32 v36, v39, v43
	v_fmac_f32_e32 v36, v38, v42
	v_add_f32_e32 v36, v37, v36
	s_waitcnt lgkmcnt(0)
	v_mul_f32_e32 v33, v33, v45
	v_fmac_f32_e32 v33, v32, v44
	v_mul_f32_e32 v32, v35, v47
	v_fmac_f32_e32 v32, v34, v46
	v_add_f32_e32 v32, v33, v32
	v_add_f32_e32 v32, v36, v32
	v_add_f32_e32 v36, v40, v32
	ds_read_b128 v[32:35], v63 offset:768
	s_waitcnt vmcnt(4)
	v_lshlrev_b32_e32 v37, 16, v28
	v_and_b32_e32 v28, 0xffff0000, v28
	v_lshlrev_b32_e32 v38, 16, v29
	v_and_b32_e32 v39, 0xffff0000, v29
	v_lshlrev_b32_e32 v40, 16, v30
	v_and_b32_e32 v41, 0xffff0000, v30
	v_lshlrev_b32_e32 v42, 16, v31
	v_and_b32_e32 v43, 0xffff0000, v31
	s_waitcnt lgkmcnt(0)
	v_mul_f32_e32 v33, v33, v28
	ds_read_b128 v[28:31], v63 offset:784
	v_fmac_f32_e32 v33, v32, v37
	v_mul_f32_e32 v32, v35, v39
	v_fmac_f32_e32 v32, v34, v38
	v_add_f32_e32 v32, v33, v32
	s_waitcnt lgkmcnt(0)
	v_mul_f32_e32 v29, v29, v41
	v_fmac_f32_e32 v29, v28, v40
	v_mul_f32_e32 v28, v31, v43
	v_fmac_f32_e32 v28, v30, v42
	v_add_f32_e32 v28, v29, v28
	v_add_f32_e32 v28, v32, v28
	v_add_f32_e32 v32, v36, v28
	ds_read_b128 v[28:31], v63 offset:800
	v_lshlrev_b32_e32 v33, 16, v24
	v_and_b32_e32 v24, 0xffff0000, v24
	v_lshlrev_b32_e32 v34, 16, v25
	v_and_b32_e32 v25, 0xffff0000, v25
	s_waitcnt lgkmcnt(0)
	v_mul_f32_e32 v24, v29, v24
	v_fmac_f32_e32 v24, v28, v33
	v_add_u32_e32 v28, s90, v48
	v_mul_f32_e32 v25, v31, v25
	v_ashrrev_i32_e32 v29, 31, v28
	v_fmac_f32_e32 v25, v30, v34
	v_lshlrev_b64 v[30:31], 2, v[28:29]
	v_lshl_add_u64 v[28:29], s[10:11], 0, v[30:31]
	global_load_dword v34, v[28:29], off
	v_lshlrev_b32_e32 v35, 16, v26
	v_and_b32_e32 v36, 0xffff0000, v26
	v_lshlrev_b32_e32 v37, 16, v27
	v_and_b32_e32 v38, 0xffff0000, v27
	v_add_f32_e32 v33, v24, v25
	ds_read_b128 v[24:27], v63 offset:816
	v_lshlrev_b32_e32 v39, 16, v23
	v_and_b32_e32 v40, 0xffff0000, v23
	v_lshl_add_u64 v[30:31], s[4:5], 0, v[30:31]
	s_waitcnt lgkmcnt(0)
	v_mul_f32_e32 v25, v25, v36
	v_fmac_f32_e32 v25, v24, v35
	v_mul_f32_e32 v24, v27, v38
	v_fmac_f32_e32 v24, v26, v37
	v_add_f32_e32 v24, v25, v24
	v_add_f32_e32 v24, v33, v24
	v_add_f32_e32 v32, v32, v24
	ds_read_b128 v[24:27], v63 offset:832
	v_lshlrev_b32_e32 v33, 16, v20
	v_and_b32_e32 v20, 0xffff0000, v20
	v_lshlrev_b32_e32 v35, 16, v21
	v_and_b32_e32 v36, 0xffff0000, v21
	v_lshlrev_b32_e32 v37, 16, v22
	v_and_b32_e32 v38, 0xffff0000, v22
	s_waitcnt lgkmcnt(0)
; __device__ __forceinline__ unsigned cvt_pk_bf16(float lo, float hi) { const f32x2cv v = {lo, hi}; return __builtin_bit_cast(unsigned, __builtin_convertvector(v, bf16x2cv)); }
; #define LAS __attribute__((address_space(3)))
; __device__ __forceinline__ float silu_f(float x) { return x * __builtin_amdgcn_rcpf(1.f + __builtin_amdgcn_exp2f(-1.4426950408889634f * x)); }
; __device__ __forceinline__ float dot4(f32x4 a, f32x4 b) { return (a[0] * b[0] + a[1] * b[1]) + (a[2] * b[2] + a[3] * b[3]); }
; __device__ __forceinline__ void unpack8(u32x4 w, f32x4& a, f32x4& b) { a = (f32x4){bflo(w.x), bfhi(w.x), bflo(w.y), bfhi(w.y)}; b = (f32x4){bflo(w.z), bfhi(w.z), bflo(w.w), bfhi(w.w)}; }
; __device__ __forceinline__ void sample_mix_even(Frame& F0, int j, int b) {
;     ...
;             for (int i = 0; i < 16; ++i) pr[i] = *(const u32x4*)(pm + hb * 128 + i * 8);
; #pragma unroll
;             for (int i = 0; i < 16; ++i) { f32x4 p0, p1; unpack8(pr[i], p0, p1); const LAS float* q = pg + hb * 128 + i * 8; a += dot4(p0, *(const LAS f32x4*)q) + dot4(p1, *(const LAS f32x4*)(q + 4)); }
;         }
;         const float ya = a * FIN(12)[j * 1024 + d] * silu_f(z[1024 + d]);
;         const float vn = vv[k] * rv * FIN(15)[j * 1024 + d];
;         F.out[O_SGUV + (size_t)(j * 128 + b) * 1024 + d] = vn;
;         const float mixed = FIN(13)[(size_t)(j * 4 + g) * 16384] * vn + FIN(14)[(j * 4 + g) * 128];
;         const float yb = z[2048 + d] * mixed * silu_f(z[4096 + d]);
;         ((bf16_t*)(F.ws + WS_SA2))[(size_t)b * 2048 + d] = (bf16_t)(cvt_pk_bf16(ya, 0.f) & 0xffffu); ((bf16_t*)(F.ws + WS_SA2))[(size_t)b * 2048 + 1024 + d] = (bf16_t)(cvt_pk_bf16(yb, 0.f) & 0xffffu);
	v_mul_f32_e32 v25, v25, v20
	ds_read_b128 v[20:23], v63 offset:848
	v_fmac_f32_e32 v25, v24, v33
	v_mul_f32_e32 v24, v27, v36
	v_fmac_f32_e32 v24, v26, v35
	v_add_f32_e32 v24, v25, v24
	s_waitcnt lgkmcnt(0)
	v_mul_f32_e32 v21, v21, v38
	v_fmac_f32_e32 v21, v20, v37
	v_mul_f32_e32 v20, v23, v40
	v_fmac_f32_e32 v20, v22, v39
	v_add_f32_e32 v20, v21, v20
	v_add_f32_e32 v20, v24, v20
	v_add_f32_e32 v24, v32, v20
	ds_read_b128 v[20:23], v63 offset:864
	v_lshlrev_b32_e32 v25, 16, v16
	v_and_b32_e32 v16, 0xffff0000, v16
	v_lshlrev_b32_e32 v26, 16, v17
	v_and_b32_e32 v27, 0xffff0000, v17
	v_lshlrev_b32_e32 v32, 16, v18
	v_and_b32_e32 v33, 0xffff0000, v18
	v_lshlrev_b32_e32 v35, 16, v19
	v_and_b32_e32 v36, 0xffff0000, v19
	s_waitcnt lgkmcnt(0)
	v_mul_f32_e32 v21, v21, v16
	ds_read_b128 v[16:19], v63 offset:880
	v_fmac_f32_e32 v21, v20, v25
	v_mul_f32_e32 v20, v23, v27
	v_fmac_f32_e32 v20, v22, v26
	v_add_f32_e32 v20, v21, v20
	s_waitcnt lgkmcnt(0)
	v_mul_f32_e32 v17, v17, v33
	v_fmac_f32_e32 v17, v16, v32
	v_mul_f32_e32 v16, v19, v36
	v_fmac_f32_e32 v16, v18, v35
	v_add_f32_e32 v16, v17, v16
	v_add_f32_e32 v16, v20, v16
	v_add_f32_e32 v20, v24, v16
	ds_read_b128 v[16:19], v63 offset:896
	s_waitcnt vmcnt(1)
	v_lshlrev_b32_e32 v21, 16, v12
	v_and_b32_e32 v12, 0xffff0000, v12
	v_lshlrev_b32_e32 v22, 16, v13
	v_and_b32_e32 v23, 0xffff0000, v13
	v_lshlrev_b32_e32 v24, 16, v14
	v_and_b32_e32 v25, 0xffff0000, v14
	v_lshlrev_b32_e32 v26, 16, v15
	v_and_b32_e32 v27, 0xffff0000, v15
	s_waitcnt lgkmcnt(0)
	v_mul_f32_e32 v17, v17, v12
	ds_read_b128 v[12:15], v63 offset:912
	v_fmac_f32_e32 v17, v16, v21
	v_mul_f32_e32 v16, v19, v23
	v_fmac_f32_e32 v16, v18, v22
	v_add_f32_e32 v18, v17, v16
	s_waitcnt lgkmcnt(0)
	v_mul_f32_e32 v13, v13, v25
	v_fmac_f32_e32 v13, v12, v24
	v_mul_f32_e32 v12, v15, v27
	v_fmac_f32_e32 v12, v14, v26
	v_add_f32_e32 v19, v13, v12
	v_add_co_u32_e32 v14, vcc, s70, v50
	v_mul_f32_e32 v12, v60, v59
	s_nop 0
	v_addc_co_u32_e32 v15, vcc, 0, v51, vcc
	s_waitcnt vmcnt(0)
	v_mul_f32_e32 v23, v12, v34
	v_lshl_add_u64 v[12:13], v[48:49], 2, s[2:3]
	s_mov_b32 s2, 0x54b0000
	v_add_co_u32_e32 v16, vcc, s2, v12
	global_load_dword v21, v[30:31], off
	s_nop 0
	v_addc_co_u32_e32 v17, vcc, 0, v13, vcc
	global_load_dword v22, v[14:15], off offset:-4096
	v_add_f32_e32 v18, v18, v19
	global_store_dword v[16:17], v23, off
	v_add_co_u32_e32 v16, vcc, s94, v50
	v_add_f32_e32 v18, v20, v18
	s_nop 0
	v_addc_co_u32_e32 v17, vcc, 0, v51, vcc
	global_load_dword v24, v[16:17], off
	v_lshlrev_b64 v[16:17], 16, v[54:55]
	v_lshl_add_u64 v[16:17], s[6:7], 0, v[16:17]
	global_load_dword v19, v[16:17], off
	v_lshlrev_b32_e32 v16, 7, v54
	v_ashrrev_i32_e32 v17, 31, v16
	v_lshl_add_u64 v[16:17], v[16:17], 2, s[8:9]
	global_load_dword v25, v[16:17], off
	global_load_dword v26, v[14:15], off
	ds_read_b128 v[14:17], v63 offset:928
	v_lshlrev_b32_e32 v20, 16, v8
	v_and_b32_e32 v8, 0xffff0000, v8
	v_lshlrev_b32_e32 v27, 16, v9
	v_and_b32_e32 v32, 0xffff0000, v9
	v_lshlrev_b32_e32 v33, 16, v10
	v_and_b32_e32 v34, 0xffff0000, v10
	v_lshlrev_b32_e32 v35, 16, v11
	v_and_b32_e32 v36, 0xffff0000, v11
	s_waitcnt lgkmcnt(0)
	v_mul_f32_e32 v15, v15, v8
	ds_read_b128 v[8:11], v63 offset:944
	v_fmac_f32_e32 v15, v14, v20
	v_mul_f32_e32 v14, v17, v32
	v_fmac_f32_e32 v14, v16, v27
	v_add_f32_e32 v14, v15, v14
	s_waitcnt lgkmcnt(0)
	v_mul_f32_e32 v9, v9, v34
	v_fmac_f32_e32 v9, v8, v33
	v_mul_f32_e32 v8, v11, v36
	v_fmac_f32_e32 v8, v10, v35
	v_add_f32_e32 v8, v9, v8
	v_add_f32_e32 v8, v14, v8
	v_add_f32_e32 v14, v18, v8
	ds_read_b128 v[8:11], v63 offset:960
	v_lshlrev_b32_e32 v15, 16, v4
	v_and_b32_e32 v4, 0xffff0000, v4
	v_lshlrev_b32_e32 v16, 16, v5
	v_and_b32_e32 v17, 0xffff0000, v5
	v_lshlrev_b32_e32 v18, 16, v6
	v_and_b32_e32 v20, 0xffff0000, v6
	v_lshlrev_b32_e32 v27, 16, v7
	v_and_b32_e32 v32, 0xffff0000, v7
	s_waitcnt lgkmcnt(0)
	v_mul_f32_e32 v9, v9, v4
	ds_read_b128 v[4:7], v63 offset:976
	v_fmac_f32_e32 v9, v8, v15
	v_mul_f32_e32 v8, v11, v17
	v_fmac_f32_e32 v8, v10, v16
	v_add_f32_e32 v8, v9, v8
	s_waitcnt lgkmcnt(0)
	v_mul_f32_e32 v5, v5, v20
	v_fmac_f32_e32 v5, v4, v18
	v_mul_f32_e32 v4, v7, v32
	v_fmac_f32_e32 v4, v6, v27
	v_add_f32_e32 v4, v5, v4
	v_add_f32_e32 v4, v8, v4
	v_add_f32_e32 v8, v14, v4
	ds_read_b128 v[4:7], v63 offset:992
	v_lshlrev_b32_e32 v9, 16, v0
	v_and_b32_e32 v0, 0xffff0000, v0
	v_lshlrev_b32_e32 v10, 16, v1
	v_and_b32_e32 v11, 0xffff0000, v1
	v_lshlrev_b32_e32 v14, 16, v2
	v_and_b32_e32 v15, 0xffff0000, v2
	v_lshlrev_b32_e32 v16, 16, v3
	v_and_b32_e32 v17, 0xffff0000, v3
	s_waitcnt lgkmcnt(0)
	v_mul_f32_e32 v5, v5, v0
	ds_read_b128 v[0:3], v63 offset:1008
	v_fmac_f32_e32 v5, v4, v9
	v_mul_f32_e32 v4, v7, v11
	v_fmac_f32_e32 v4, v6, v10
	v_add_f32_e32 v4, v5, v4
	s_waitcnt lgkmcnt(0)
	v_mul_f32_e32 v1, v1, v15
	v_fmac_f32_e32 v1, v0, v14
	v_mul_f32_e32 v0, v3, v17
	v_fmac_f32_e32 v0, v2, v16
	v_add_f32_e32 v0, v1, v0
	s_waitcnt vmcnt(5)
	v_mul_f32_e32 v3, 0xbfb8aa3b, v22
	v_exp_f32_e32 v3, v3
	v_add_f32_e32 v0, v4, v0
	v_add_f32_e32 v0, v8, v0
	v_mul_f32_e32 v0, v21, v0
	v_add_f32_e32 v1, 1.0, v3
	v_rcp_f32_e32 v1, v1
	s_waitcnt vmcnt(3)
	v_mul_f32_e32 v2, 0xbfb8aa3b, v24
	v_exp_f32_e32 v2, v2
	v_mul_f32_e32 v1, v22, v1
	v_mul_f32_e32 v0, v0, v1
	v_cvt_pk_bf16_f32 v3, v0, s0
	v_add_f32_e32 v2, 1.0, v2
	v_rcp_f32_e32 v2, v2
	s_waitcnt vmcnt(1)
	v_fmac_f32_e32 v25, v23, v19
	s_waitcnt vmcnt(0)
	v_mul_f32_e32 v1, v26, v25
	v_mul_f32_e32 v2, v24, v2
	v_mul_f32_e32 v2, v1, v2
	v_lshl_add_u64 v[0:1], v[48:49], 1, s[0:1]
	s_mov_b64 s[0:1], 0x1b500000
	v_lshl_add_u64 v[20:21], v[0:1], 0, s[0:1]
	s_mov_b32 s0, 0x1b500000
	v_add_co_u32_e32 v0, vcc, s0, v0
	s_nop 0
	v_addc_co_u32_e32 v1, vcc, 0, v1, vcc
	global_store_short v[0:1], v3, off
	v_cvt_pk_bf16_f32 v0, v2, s0
	global_store_short v[20:21], v0, off offset:2048
	s_mov_b64 s[0:1], 0x800
	s_mov_b64 s[0:1], 0x54b0000
	s_waitcnt vmcnt(0)
; #define LAS __attribute__((address_space(3)))
; __device__ __forceinline__ void sample_mix_even(Frame& F0, int j, int b) {
;     ...
;     float tot = 0.f;
; #pragma unroll
;     for (int i = 0; i < 8; ++i) tot += red[i];
;     const float rv = rsqrtf(tot * (1.0f / D) + EPS);
; #pragma unroll
;     for (int k = 0; k < 2; ++k) {
;         const int d = tid + 512 * k, g = d >> 8, dd = d & 255;
;         const bf16_t* pm = ((bf16_t*)(F.ws + WS_PMT)) + (size_t)(j * 4 + g) * 65536 + (size_t)dd * 256; const LAS float* pg = pl + g * 256;
;         float a = 0.f;
; #pragma unroll
;         for (int hb = 0; hb < 2; ++hb) {
;             u32x4 pr[16];
; #pragma unroll
;             for (int i = 0; i < 16; ++i) pr[i] = *(const u32x4*)(pm + hb * 128 + i * 8);
	s_waitcnt lgkmcnt(0)
	s_waitcnt lgkmcnt(0)
	s_waitcnt vmcnt(0)
	s_waitcnt lgkmcnt(0)
	s_waitcnt lgkmcnt(0)
	s_waitcnt vmcnt(0)
	s_waitcnt lgkmcnt(0)
	s_waitcnt lgkmcnt(0)
	s_waitcnt vmcnt(0)
	s_waitcnt lgkmcnt(0)
	s_waitcnt lgkmcnt(0)
	s_waitcnt vmcnt(0)
	s_waitcnt lgkmcnt(0)
	s_waitcnt lgkmcnt(0)
	s_waitcnt lgkmcnt(0)
	s_waitcnt lgkmcnt(0)
	s_waitcnt lgkmcnt(0)
	s_waitcnt lgkmcnt(0)
	s_waitcnt lgkmcnt(0)
	s_waitcnt lgkmcnt(0)
	s_waitcnt vmcnt(0)
	s_waitcnt lgkmcnt(0)
	s_waitcnt lgkmcnt(0)
	s_waitcnt lgkmcnt(0)
	s_waitcnt lgkmcnt(0)
	s_waitcnt lgkmcnt(0)
	s_waitcnt lgkmcnt(0)
	s_waitcnt lgkmcnt(0)
	s_waitcnt lgkmcnt(0)
	s_waitcnt vmcnt(0)
	s_waitcnt lgkmcnt(0)
	s_waitcnt lgkmcnt(0)
	s_waitcnt lgkmcnt(0)
	s_waitcnt lgkmcnt(0)
	s_waitcnt lgkmcnt(0)
	s_waitcnt lgkmcnt(0)
	s_waitcnt lgkmcnt(0)
	s_waitcnt lgkmcnt(0)
	s_waitcnt vmcnt(0)
	s_waitcnt lgkmcnt(0)
	s_waitcnt lgkmcnt(0)
	s_waitcnt vmcnt(0)
	s_waitcnt lgkmcnt(0)
	s_waitcnt lgkmcnt(0)
	s_waitcnt vmcnt(0)
	s_waitcnt lgkmcnt(0)
	s_waitcnt lgkmcnt(0)
	s_waitcnt vmcnt(0)
	s_waitcnt lgkmcnt(0)
	s_waitcnt lgkmcnt(0)
	s_waitcnt vmcnt(0)
	s_waitcnt lgkmcnt(0)
	s_waitcnt lgkmcnt(0)
	s_waitcnt lgkmcnt(0)
	s_waitcnt lgkmcnt(0)
	s_waitcnt lgkmcnt(0)
	s_waitcnt lgkmcnt(0)
	s_waitcnt lgkmcnt(0)
	s_waitcnt lgkmcnt(0)
	s_waitcnt vmcnt(0)
	s_waitcnt lgkmcnt(0)
	s_waitcnt lgkmcnt(0)
	s_waitcnt lgkmcnt(0)
	s_waitcnt lgkmcnt(0)
	s_waitcnt lgkmcnt(0)
	s_waitcnt lgkmcnt(0)
	s_waitcnt lgkmcnt(0)
	s_waitcnt lgkmcnt(0)
	s_waitcnt vmcnt(0)
	s_waitcnt lgkmcnt(0)
	s_waitcnt lgkmcnt(0)
	s_nop 0
	s_waitcnt vmcnt(0)
	s_nop 0
	s_waitcnt lgkmcnt(0)
	s_waitcnt lgkmcnt(0)
	s_waitcnt lgkmcnt(0)
	s_waitcnt lgkmcnt(0)
	s_waitcnt lgkmcnt(0)
	s_waitcnt lgkmcnt(0)
	s_waitcnt vmcnt(0)
	s_waitcnt vmcnt(0)
	s_waitcnt vmcnt(0)
	s_waitcnt vmcnt(0)
	s_branch .Lsmx_end
.Lsmx_hi:
	ds_read_b128 v[0:3], v201 offset:4096
	ds_read_b128 v[4:7], v201 offset:4112
	s_mov_b32 s4, 0x800000
	s_waitcnt lgkmcnt(1)
	v_add_f32_e32 v0, 0, v0
	v_add_f32_e32 v0, v0, v1
	v_add_f32_e32 v0, v0, v2
	v_add_f32_e32 v0, v0, v3
	s_waitcnt lgkmcnt(0)
	v_add_f32_e32 v0, v0, v4
	v_add_f32_e32 v0, v0, v5
	v_add_f32_e32 v0, v0, v6
	v_add_f32_e32 v0, v0, v7
	v_mov_b32_e32 v1, 0x358637bd
	v_fmamk_f32 v0, v0, 0x3a800000, v1
	v_cmp_gt_f32_e32 vcc, s4, v0
	v_mul_f32_e32 v1, 0x4b800000, v0
	s_load_dwordx8 s[4:11], s[14:15], 0x60
	v_cndmask_b32_e32 v0, v0, v1, vcc
	v_rsq_f32_e32 v0, v0
	s_lshl_b64 s[14:15], s[16:17], 12
	s_add_u32 s2, s2, s14
	s_addc_u32 s3, s3, s15
	v_mul_f32_e32 v1, 0x45800000, v0
	v_cndmask_b32_e32 v59, v0, v1, vcc
	s_lshl_b64 s[0:1], s[0:1], 12
	s_add_u32 s0, s12, s0
	s_addc_u32 s1, s13, s1
	s_add_i32 s93, s93, s22
	s_cmp_lt_i32 s93, 16
	s_waitcnt vmcnt(0)
	s_waitcnt lgkmcnt(0)
	s_waitcnt vmcnt(0)
	s_waitcnt vmcnt(0)
	s_waitcnt lgkmcnt(0)
	s_waitcnt lgkmcnt(0)
	s_waitcnt vmcnt(0)
	s_waitcnt lgkmcnt(0)
	s_waitcnt lgkmcnt(0)
	s_waitcnt vmcnt(0)
	s_waitcnt lgkmcnt(0)
	s_waitcnt lgkmcnt(0)
	s_waitcnt lgkmcnt(0)
	s_waitcnt lgkmcnt(0)
	s_waitcnt lgkmcnt(0)
	s_waitcnt lgkmcnt(0)
	s_waitcnt lgkmcnt(0)
	s_waitcnt lgkmcnt(0)
	s_waitcnt vmcnt(0)
	s_waitcnt lgkmcnt(0)
	s_waitcnt lgkmcnt(0)
	s_waitcnt lgkmcnt(0)
	s_waitcnt lgkmcnt(0)
	s_waitcnt lgkmcnt(0)
	s_waitcnt lgkmcnt(0)
	s_waitcnt lgkmcnt(0)
	s_waitcnt lgkmcnt(0)
	s_waitcnt vmcnt(0)
	s_waitcnt lgkmcnt(0)
	s_waitcnt lgkmcnt(0)
	s_waitcnt lgkmcnt(0)
	s_waitcnt lgkmcnt(0)
	s_waitcnt lgkmcnt(0)
	s_waitcnt lgkmcnt(0)
	s_waitcnt lgkmcnt(0)
	s_waitcnt lgkmcnt(0)
	s_waitcnt vmcnt(0)
	s_waitcnt lgkmcnt(0)
	s_waitcnt lgkmcnt(0)
	s_waitcnt vmcnt(0)
	s_waitcnt lgkmcnt(0)
	s_waitcnt lgkmcnt(0)
	s_waitcnt vmcnt(0)
	s_waitcnt lgkmcnt(0)
	s_waitcnt lgkmcnt(0)
	s_waitcnt vmcnt(0)
	s_waitcnt lgkmcnt(0)
	s_waitcnt lgkmcnt(0)
	s_waitcnt vmcnt(0)
	s_waitcnt lgkmcnt(0)
	s_waitcnt lgkmcnt(0)
	s_waitcnt lgkmcnt(0)
	s_waitcnt lgkmcnt(0)
	s_waitcnt lgkmcnt(0)
	s_waitcnt lgkmcnt(0)
	s_waitcnt lgkmcnt(0)
	s_waitcnt lgkmcnt(0)
	s_waitcnt vmcnt(0)
	s_waitcnt lgkmcnt(0)
	s_waitcnt lgkmcnt(0)
	s_waitcnt lgkmcnt(0)
	v_add_u32_e32 v28, s90, v48
	v_ashrrev_i32_e32 v29, 31, v28
	v_lshlrev_b64 v[30:31], 2, v[28:29]
	v_lshl_add_u64 v[28:29], s[10:11], 0, v[30:31]
	v_lshl_add_u64 v[30:31], s[4:5], 0, v[30:31]
	s_waitcnt lgkmcnt(0)
	s_waitcnt lgkmcnt(0)
	s_waitcnt lgkmcnt(0)
	s_waitcnt lgkmcnt(0)
	s_waitcnt lgkmcnt(0)
	s_waitcnt vmcnt(0)
	s_waitcnt lgkmcnt(0)
	s_waitcnt lgkmcnt(0)
	s_nop 0
	s_waitcnt vmcnt(0)
	v_lshl_add_u64 v[12:13], v[48:49], 2, s[2:3]
	s_mov_b32 s2, 0x54b0000
	s_nop 0
	s_nop 0
	s_waitcnt lgkmcnt(0)
	s_waitcnt lgkmcnt(0)
	s_waitcnt lgkmcnt(0)
	s_waitcnt lgkmcnt(0)
	s_waitcnt lgkmcnt(0)
	s_waitcnt lgkmcnt(0)
	s_waitcnt vmcnt(0)
	s_waitcnt vmcnt(0)
	s_waitcnt vmcnt(0)
	s_waitcnt vmcnt(0)
	v_add_u32_e32 v22, s24, v62
	v_lshl_add_u64 v[0:1], v[48:49], 1, s[0:1]
	s_mov_b64 s[0:1], 0x1b500000
	v_lshl_add_u64 v[20:21], v[0:1], 0, s[0:1]
	s_mov_b32 s0, 0x1b500000
	v_ashrrev_i32_e32 v23, 31, v22
	s_nop 0
	v_lshlrev_b64 v[0:1], 17, v[22:23]
	v_lshl_add_u64 v[32:33], v[52:53], 0, v[0:1]
	global_load_dwordx4 v[36:39], v[32:33], off
	global_load_dwordx4 v[40:43], v[32:33], off offset:16
	global_load_dwordx4 v[44:47], v[32:33], off offset:32
	s_mov_b64 s[0:1], 0x800
	v_lshl_add_u64 v[24:25], v[50:51], 0, s[0:1]
	global_load_dwordx4 v[48:51], v[32:33], off offset:48
	s_mov_b64 s[0:1], 0x54b0000
	v_and_b32_e32 v0, 0x3fffff00, v61
	v_lshl_add_u64 v[26:27], v[12:13], 0, s[0:1]
	v_lshl_add_u32 v34, v0, 2, 0
	global_load_dwordx4 v[52:55], v[32:33], off offset:112
	global_load_dwordx4 v[60:63], v[32:33], off offset:96
	global_load_dwordx4 v[64:67], v[32:33], off offset:80
	global_load_dwordx4 v[68:71], v[32:33], off offset:64
	global_load_dwordx4 v[16:19], v[32:33], off offset:176
	global_load_dwordx4 v[72:75], v[32:33], off offset:160
	global_load_dwordx4 v[76:79], v[32:33], off offset:144
	global_load_dwordx4 v[80:83], v[32:33], off offset:128
	global_load_dwordx4 v[0:3], v[32:33], off offset:240
	global_load_dwordx4 v[4:7], v[32:33], off offset:224
	global_load_dwordx4 v[8:11], v[32:33], off offset:208
	global_load_dwordx4 v[12:15], v[32:33], off offset:192
	ds_read_b128 v[84:87], v34
	s_waitcnt vmcnt(15)
; #define LAS __attribute__((address_space(3)))
; __device__ __forceinline__ float dot4(f32x4 a, f32x4 b) { return (a[0] * b[0] + a[1] * b[1]) + (a[2] * b[2] + a[3] * b[3]); }
; __device__ __forceinline__ void unpack8(u32x4 w, f32x4& a, f32x4& b) { a = (f32x4){bflo(w.x), bfhi(w.x), bflo(w.y), bfhi(w.y)}; b = (f32x4){bflo(w.z), bfhi(w.z), bflo(w.w), bfhi(w.w)}; }
; __device__ __forceinline__ void sample_mix_even(Frame& F0, int j, int b) {
;     ...
; #pragma unroll
;         for (int hb = 0; hb < 2; ++hb) {
;             u32x4 pr[16];
; #pragma unroll
;             for (int i = 0; i < 16; ++i) pr[i] = *(const u32x4*)(pm + hb * 128 + i * 8);
; #pragma unroll
;             for (int i = 0; i < 16; ++i) { f32x4 p0, p1; unpack8(pr[i], p0, p1); const LAS float* q = pg + hb * 128 + i * 8; a += dot4(p0, *(const LAS f32x4*)q) + dot4(p1, *(const LAS f32x4*)(q + 4)); }
	v_lshlrev_b32_e32 v35, 16, v36
	v_and_b32_e32 v56, 0xffff0000, v36
	v_lshlrev_b32_e32 v57, 16, v37
	v_and_b32_e32 v96, 0xffff0000, v37
	v_lshlrev_b32_e32 v97, 16, v38
	v_and_b32_e32 v98, 0xffff0000, v38
	v_lshlrev_b32_e32 v99, 16, v39
	v_and_b32_e32 v100, 0xffff0000, v39
	ds_read_b128 v[36:39], v34 offset:16
	ds_read_b128 v[88:91], v34 offset:32
	ds_read_b128 v[92:95], v34 offset:48
	s_waitcnt lgkmcnt(3)
	v_mul_f32_e32 v56, v85, v56
	v_fmac_f32_e32 v56, v84, v35
	s_waitcnt lgkmcnt(2)
	v_mul_f32_e32 v37, v37, v98
	v_mul_f32_e32 v35, v87, v96
	v_fmac_f32_e32 v37, v36, v97
	v_mul_f32_e32 v36, v39, v100
	v_fmac_f32_e32 v35, v86, v57
	v_fmac_f32_e32 v36, v38, v99
	v_add_f32_e32 v35, v56, v35
	v_add_f32_e32 v36, v37, v36
	s_waitcnt vmcnt(14)
	v_and_b32_e32 v37, 0xffff0000, v40
	v_add_f32_e32 v35, v35, v36
	v_lshlrev_b32_e32 v36, 16, v40
	v_and_b32_e32 v39, 0xffff0000, v41
	s_waitcnt lgkmcnt(1)
	v_mul_f32_e32 v37, v89, v37
	v_lshlrev_b32_e32 v38, 16, v41
	v_fmac_f32_e32 v37, v88, v36
	v_mul_f32_e32 v36, v91, v39
	v_lshlrev_b32_e32 v40, 16, v42
	v_and_b32_e32 v41, 0xffff0000, v42
	v_lshlrev_b32_e32 v42, 16, v43
	v_and_b32_e32 v43, 0xffff0000, v43
	v_fmac_f32_e32 v36, v90, v38
	v_add_f32_e32 v36, v37, v36
	s_waitcnt lgkmcnt(0)
	v_mul_f32_e32 v37, v93, v41
	v_mul_f32_e32 v38, v95, v43
	v_fmac_f32_e32 v37, v92, v40
	v_fmac_f32_e32 v38, v94, v42
	v_add_f32_e32 v37, v37, v38
	v_add_f32_e32 v35, 0, v35
	v_add_f32_e32 v36, v36, v37
	v_add_f32_e32 v35, v35, v36
	ds_read_b128 v[36:39], v34 offset:64
	s_waitcnt vmcnt(13)
	v_and_b32_e32 v40, 0xffff0000, v44
	v_lshlrev_b32_e32 v56, 16, v44
	v_lshlrev_b32_e32 v44, 16, v45
	v_and_b32_e32 v45, 0xffff0000, v45
	s_waitcnt lgkmcnt(0)
	v_mul_f32_e32 v37, v37, v40
	ds_read_b128 v[40:43], v34 offset:80
	v_fmac_f32_e32 v37, v36, v56
	v_mul_f32_e32 v36, v39, v45
	v_lshlrev_b32_e32 v57, 16, v46
	v_and_b32_e32 v46, 0xffff0000, v46
	v_lshlrev_b32_e32 v84, 16, v47
	v_and_b32_e32 v47, 0xffff0000, v47
	v_fmac_f32_e32 v36, v38, v44
	v_add_f32_e32 v36, v37, v36
	s_waitcnt lgkmcnt(0)
	v_mul_f32_e32 v37, v41, v46
	v_mul_f32_e32 v38, v43, v47
	v_fmac_f32_e32 v37, v40, v57
	v_fmac_f32_e32 v38, v42, v84
	v_add_f32_e32 v37, v37, v38
	v_add_f32_e32 v36, v36, v37
	v_add_f32_e32 v35, v35, v36
	ds_read_b128 v[36:39], v34 offset:96
	s_waitcnt vmcnt(12)
	v_and_b32_e32 v40, 0xffff0000, v48
	v_lshlrev_b32_e32 v44, 16, v48
	v_and_b32_e32 v46, 0xffff0000, v49
	v_lshlrev_b32_e32 v45, 16, v49
	s_waitcnt lgkmcnt(0)
	v_mul_f32_e32 v37, v37, v40
	ds_read_b128 v[40:43], v34 offset:112
	v_fmac_f32_e32 v37, v36, v44
	v_mul_f32_e32 v36, v39, v46
	v_lshlrev_b32_e32 v47, 16, v50
	v_and_b32_e32 v48, 0xffff0000, v50
	v_and_b32_e32 v50, 0xffff0000, v51
	v_fmac_f32_e32 v36, v38, v45
	v_lshlrev_b32_e32 v49, 16, v51
	v_add_f32_e32 v36, v37, v36
	s_waitcnt lgkmcnt(0)
	v_mul_f32_e32 v37, v41, v48
	v_mul_f32_e32 v38, v43, v50
	v_fmac_f32_e32 v37, v40, v47
	v_fmac_f32_e32 v38, v42, v49
	v_add_f32_e32 v37, v37, v38
	v_add_f32_e32 v36, v36, v37
	v_add_f32_e32 v35, v35, v36
	ds_read_b128 v[36:39], v34 offset:128
	s_waitcnt vmcnt(8)
	v_and_b32_e32 v40, 0xffff0000, v68
	v_lshlrev_b32_e32 v44, 16, v68
	v_and_b32_e32 v46, 0xffff0000, v69
	v_lshlrev_b32_e32 v45, 16, v69
	s_waitcnt lgkmcnt(0)
	v_mul_f32_e32 v37, v37, v40
	ds_read_b128 v[40:43], v34 offset:144
	v_fmac_f32_e32 v37, v36, v44
	v_mul_f32_e32 v36, v39, v46
	v_and_b32_e32 v48, 0xffff0000, v70
	v_and_b32_e32 v50, 0xffff0000, v71
	v_fmac_f32_e32 v36, v38, v45
	v_lshlrev_b32_e32 v47, 16, v70
	v_lshlrev_b32_e32 v49, 16, v71
	v_add_f32_e32 v36, v37, v36
	s_waitcnt lgkmcnt(0)
	v_mul_f32_e32 v37, v41, v48
	v_mul_f32_e32 v38, v43, v50
	v_fmac_f32_e32 v37, v40, v47
	v_fmac_f32_e32 v38, v42, v49
	v_add_f32_e32 v37, v37, v38
	v_add_f32_e32 v36, v36, v37
	v_add_f32_e32 v35, v35, v36
	ds_read_b128 v[36:39], v34 offset:160
	v_and_b32_e32 v40, 0xffff0000, v64
	v_lshlrev_b32_e32 v44, 16, v64
	v_and_b32_e32 v46, 0xffff0000, v65
	v_lshlrev_b32_e32 v45, 16, v65
	s_waitcnt lgkmcnt(0)
	v_mul_f32_e32 v37, v37, v40
	ds_read_b128 v[40:43], v34 offset:176
	v_fmac_f32_e32 v37, v36, v44
	v_mul_f32_e32 v36, v39, v46
	v_and_b32_e32 v48, 0xffff0000, v66
	v_and_b32_e32 v50, 0xffff0000, v67
	v_fmac_f32_e32 v36, v38, v45
	v_lshlrev_b32_e32 v47, 16, v66
	v_lshlrev_b32_e32 v49, 16, v67
	v_add_f32_e32 v36, v37, v36
	s_waitcnt lgkmcnt(0)
	v_mul_f32_e32 v37, v41, v48
	v_mul_f32_e32 v38, v43, v50
	v_fmac_f32_e32 v37, v40, v47
	v_fmac_f32_e32 v38, v42, v49
	v_add_f32_e32 v37, v37, v38
	v_add_f32_e32 v36, v36, v37
	v_add_f32_e32 v35, v35, v36
	ds_read_b128 v[36:39], v34 offset:192
	v_and_b32_e32 v40, 0xffff0000, v60
	v_lshlrev_b32_e32 v44, 16, v60
	v_and_b32_e32 v46, 0xffff0000, v61
	v_lshlrev_b32_e32 v45, 16, v61
	s_waitcnt lgkmcnt(0)
	v_mul_f32_e32 v37, v37, v40
	ds_read_b128 v[40:43], v34 offset:208
	v_fmac_f32_e32 v37, v36, v44
	v_mul_f32_e32 v36, v39, v46
	v_and_b32_e32 v48, 0xffff0000, v62
	v_and_b32_e32 v50, 0xffff0000, v63
	v_fmac_f32_e32 v36, v38, v45
	v_lshlrev_b32_e32 v47, 16, v62
	v_lshlrev_b32_e32 v49, 16, v63
	v_add_f32_e32 v36, v37, v36
	s_waitcnt lgkmcnt(0)
	v_mul_f32_e32 v37, v41, v48
	v_mul_f32_e32 v38, v43, v50
	v_fmac_f32_e32 v37, v40, v47
	v_fmac_f32_e32 v38, v42, v49
	v_add_f32_e32 v37, v37, v38
	v_add_f32_e32 v36, v36, v37
	v_add_f32_e32 v35, v35, v36
	ds_read_b128 v[36:39], v34 offset:224
	v_and_b32_e32 v40, 0xffff0000, v52
	v_lshlrev_b32_e32 v44, 16, v52
	v_and_b32_e32 v46, 0xffff0000, v53
	v_lshlrev_b32_e32 v45, 16, v53
	s_waitcnt lgkmcnt(0)
	v_mul_f32_e32 v37, v37, v40
	ds_read_b128 v[40:43], v34 offset:240
	v_fmac_f32_e32 v37, v36, v44
	v_mul_f32_e32 v36, v39, v46
	v_and_b32_e32 v48, 0xffff0000, v54
	v_and_b32_e32 v50, 0xffff0000, v55
	v_fmac_f32_e32 v36, v38, v45
	v_lshlrev_b32_e32 v47, 16, v54
	v_lshlrev_b32_e32 v49, 16, v55
	v_add_f32_e32 v36, v37, v36
	s_waitcnt lgkmcnt(0)
; #define LAS __attribute__((address_space(3)))
; __device__ __forceinline__ float dot4(f32x4 a, f32x4 b) { return (a[0] * b[0] + a[1] * b[1]) + (a[2] * b[2] + a[3] * b[3]); }
; __device__ __forceinline__ void unpack8(u32x4 w, f32x4& a, f32x4& b) { a = (f32x4){bflo(w.x), bfhi(w.x), bflo(w.y), bfhi(w.y)}; b = (f32x4){bflo(w.z), bfhi(w.z), bflo(w.w), bfhi(w.w)}; }
; __device__ __forceinline__ void sample_mix_even(Frame& F0, int j, int b) {
;     ...
; #pragma unroll
;         for (int hb = 0; hb < 2; ++hb) {
;             u32x4 pr[16];
; #pragma unroll
;             for (int i = 0; i < 16; ++i) pr[i] = *(const u32x4*)(pm + hb * 128 + i * 8);
; #pragma unroll
;             for (int i = 0; i < 16; ++i) { f32x4 p0, p1; unpack8(pr[i], p0, p1); const LAS float* q = pg + hb * 128 + i * 8; a += dot4(p0, *(const LAS f32x4*)q) + dot4(p1, *(const LAS f32x4*)(q + 4)); }
	v_mul_f32_e32 v37, v41, v48
	v_mul_f32_e32 v38, v43, v50
	v_fmac_f32_e32 v37, v40, v47
	v_fmac_f32_e32 v38, v42, v49
	v_add_f32_e32 v37, v37, v38
	v_add_f32_e32 v36, v36, v37
	v_add_f32_e32 v35, v35, v36
	ds_read_b128 v[36:39], v34 offset:256
	s_waitcnt vmcnt(4)
	v_and_b32_e32 v40, 0xffff0000, v80
	v_lshlrev_b32_e32 v44, 16, v80
	v_and_b32_e32 v46, 0xffff0000, v81
	v_lshlrev_b32_e32 v45, 16, v81
	s_waitcnt lgkmcnt(0)
	v_mul_f32_e32 v37, v37, v40
	ds_read_b128 v[40:43], v34 offset:272
	v_fmac_f32_e32 v37, v36, v44
	v_mul_f32_e32 v36, v39, v46
	v_and_b32_e32 v48, 0xffff0000, v82
	v_and_b32_e32 v50, 0xffff0000, v83
	v_fmac_f32_e32 v36, v38, v45
	v_lshlrev_b32_e32 v47, 16, v82
	v_lshlrev_b32_e32 v49, 16, v83
	v_add_f32_e32 v36, v37, v36
	s_waitcnt lgkmcnt(0)
	v_mul_f32_e32 v37, v41, v48
	v_mul_f32_e32 v38, v43, v50
	v_fmac_f32_e32 v37, v40, v47
	v_fmac_f32_e32 v38, v42, v49
	v_add_f32_e32 v37, v37, v38
	v_add_f32_e32 v36, v36, v37
	v_add_f32_e32 v35, v35, v36
	ds_read_b128 v[36:39], v34 offset:288
	v_and_b32_e32 v40, 0xffff0000, v76
	v_lshlrev_b32_e32 v44, 16, v76
	v_and_b32_e32 v46, 0xffff0000, v77
	v_lshlrev_b32_e32 v45, 16, v77
	s_waitcnt lgkmcnt(0)
	v_mul_f32_e32 v37, v37, v40
	ds_read_b128 v[40:43], v34 offset:304
	v_fmac_f32_e32 v37, v36, v44
	v_mul_f32_e32 v36, v39, v46
	v_and_b32_e32 v48, 0xffff0000, v78
	v_and_b32_e32 v50, 0xffff0000, v79
	v_fmac_f32_e32 v36, v38, v45
	v_lshlrev_b32_e32 v47, 16, v78
	v_lshlrev_b32_e32 v49, 16, v79
	v_add_f32_e32 v36, v37, v36
	s_waitcnt lgkmcnt(0)
	v_mul_f32_e32 v37, v41, v48
	v_mul_f32_e32 v38, v43, v50
	v_fmac_f32_e32 v37, v40, v47
	v_fmac_f32_e32 v38, v42, v49
	v_add_f32_e32 v37, v37, v38
	v_add_f32_e32 v36, v36, v37
	v_add_f32_e32 v35, v35, v36
	ds_read_b128 v[36:39], v34 offset:320
	v_and_b32_e32 v40, 0xffff0000, v72
	v_lshlrev_b32_e32 v44, 16, v72
	v_and_b32_e32 v46, 0xffff0000, v73
	v_lshlrev_b32_e32 v45, 16, v73
	s_waitcnt lgkmcnt(0)
	v_mul_f32_e32 v37, v37, v40
	ds_read_b128 v[40:43], v34 offset:336
	v_fmac_f32_e32 v37, v36, v44
	v_mul_f32_e32 v36, v39, v46
	v_and_b32_e32 v48, 0xffff0000, v74
	v_and_b32_e32 v50, 0xffff0000, v75
	v_fmac_f32_e32 v36, v38, v45
	v_lshlrev_b32_e32 v47, 16, v74
	v_lshlrev_b32_e32 v49, 16, v75
	v_add_f32_e32 v36, v37, v36
	s_waitcnt lgkmcnt(0)
	v_mul_f32_e32 v37, v41, v48
	v_mul_f32_e32 v38, v43, v50
	v_fmac_f32_e32 v37, v40, v47
	v_fmac_f32_e32 v38, v42, v49
	v_add_f32_e32 v37, v37, v38
	v_add_f32_e32 v36, v36, v37
	v_add_f32_e32 v35, v35, v36
	ds_read_b128 v[36:39], v34 offset:352
	v_lshlrev_b32_e32 v40, 16, v16
	v_and_b32_e32 v16, 0xffff0000, v16
	v_lshlrev_b32_e32 v41, 16, v17
	v_and_b32_e32 v42, 0xffff0000, v17
	v_lshlrev_b32_e32 v43, 16, v18
	v_and_b32_e32 v44, 0xffff0000, v18
	v_lshlrev_b32_e32 v45, 16, v19
	v_and_b32_e32 v46, 0xffff0000, v19
	s_waitcnt lgkmcnt(0)
	v_mul_f32_e32 v37, v37, v16
	ds_read_b128 v[16:19], v34 offset:368
	v_fmac_f32_e32 v37, v36, v40
	v_mul_f32_e32 v36, v39, v42
	v_fmac_f32_e32 v36, v38, v41
	v_add_f32_e32 v36, v37, v36
	s_waitcnt lgkmcnt(0)
	v_mul_f32_e32 v17, v17, v44
	v_fmac_f32_e32 v17, v16, v43
	v_mul_f32_e32 v16, v19, v46
	v_fmac_f32_e32 v16, v18, v45
	v_add_f32_e32 v16, v17, v16
	v_add_f32_e32 v16, v36, v16
	v_add_f32_e32 v35, v35, v16
	ds_read_b128 v[16:19], v34 offset:384
	s_waitcnt vmcnt(0)
	v_lshlrev_b32_e32 v36, 16, v12
	v_and_b32_e32 v12, 0xffff0000, v12
	v_lshlrev_b32_e32 v37, 16, v13
	v_and_b32_e32 v38, 0xffff0000, v13
	v_lshlrev_b32_e32 v39, 16, v14
	v_and_b32_e32 v40, 0xffff0000, v14
	v_lshlrev_b32_e32 v41, 16, v15
	v_and_b32_e32 v42, 0xffff0000, v15
	s_waitcnt lgkmcnt(0)
	v_mul_f32_e32 v17, v17, v12
	ds_read_b128 v[12:15], v34 offset:400
	v_fmac_f32_e32 v17, v16, v36
	v_mul_f32_e32 v16, v19, v38
	v_fmac_f32_e32 v16, v18, v37
	v_add_f32_e32 v16, v17, v16
	s_waitcnt lgkmcnt(0)
	v_mul_f32_e32 v13, v13, v40
	v_fmac_f32_e32 v13, v12, v39
	v_mul_f32_e32 v12, v15, v42
	v_fmac_f32_e32 v12, v14, v41
	v_add_f32_e32 v12, v13, v12
	v_add_f32_e32 v12, v16, v12
	v_add_f32_e32 v16, v35, v12
	ds_read_b128 v[12:15], v34 offset:416
	global_load_dwordx4 v[36:39], v[32:33], off offset:256
	v_lshlrev_b32_e32 v17, 16, v8
	v_and_b32_e32 v8, 0xffff0000, v8
	v_lshlrev_b32_e32 v18, 16, v9
	v_and_b32_e32 v19, 0xffff0000, v9
	v_lshlrev_b32_e32 v35, 16, v10
	v_and_b32_e32 v40, 0xffff0000, v10
	v_lshlrev_b32_e32 v41, 16, v11
	v_and_b32_e32 v42, 0xffff0000, v11
	s_waitcnt lgkmcnt(0)
	v_mul_f32_e32 v13, v13, v8
	ds_read_b128 v[8:11], v34 offset:432
	v_fmac_f32_e32 v13, v12, v17
	v_mul_f32_e32 v12, v15, v19
	v_fmac_f32_e32 v12, v14, v18
	v_add_f32_e32 v12, v13, v12
	s_waitcnt lgkmcnt(0)
	v_mul_f32_e32 v9, v9, v40
	v_fmac_f32_e32 v9, v8, v35
	v_mul_f32_e32 v8, v11, v42
	v_fmac_f32_e32 v8, v10, v41
	global_load_dwordx4 v[40:43], v[32:33], off offset:272
	v_add_f32_e32 v8, v9, v8
	v_add_f32_e32 v8, v12, v8
	v_add_f32_e32 v12, v16, v8
	ds_read_b128 v[8:11], v34 offset:448
	global_load_dwordx4 v[44:47], v[32:33], off offset:288
	v_lshlrev_b32_e32 v13, 16, v4
	v_and_b32_e32 v4, 0xffff0000, v4
	v_lshlrev_b32_e32 v14, 16, v5
	v_and_b32_e32 v15, 0xffff0000, v5
	v_lshlrev_b32_e32 v16, 16, v6
	v_and_b32_e32 v17, 0xffff0000, v6
	v_lshlrev_b32_e32 v18, 16, v7
	v_and_b32_e32 v19, 0xffff0000, v7
	s_waitcnt lgkmcnt(0)
	v_mul_f32_e32 v9, v9, v4
	ds_read_b128 v[4:7], v34 offset:464
	v_fmac_f32_e32 v9, v8, v13
	v_mul_f32_e32 v8, v11, v15
	v_fmac_f32_e32 v8, v10, v14
	global_load_dwordx4 v[48:51], v[32:33], off offset:304
	s_waitcnt lgkmcnt(0)
; #define LAS __attribute__((address_space(3)))
; __device__ __forceinline__ float silu_f(float x) { return x * __builtin_amdgcn_rcpf(1.f + __builtin_amdgcn_exp2f(-1.4426950408889634f * x)); }
; __device__ __forceinline__ float dot4(f32x4 a, f32x4 b) { return (a[0] * b[0] + a[1] * b[1]) + (a[2] * b[2] + a[3] * b[3]); }
; __device__ __forceinline__ void unpack8(u32x4 w, f32x4& a, f32x4& b) { a = (f32x4){bflo(w.x), bfhi(w.x), bflo(w.y), bfhi(w.y)}; b = (f32x4){bflo(w.z), bfhi(w.z), bflo(w.w), bfhi(w.w)}; }
; __device__ __forceinline__ void sample_mix_even(Frame& F0, int j, int b) {
;     ...
; #pragma unroll
;         for (int hb = 0; hb < 2; ++hb) {
;             u32x4 pr[16];
; #pragma unroll
;             for (int i = 0; i < 16; ++i) pr[i] = *(const u32x4*)(pm + hb * 128 + i * 8);
; #pragma unroll
;             for (int i = 0; i < 16; ++i) { f32x4 p0, p1; unpack8(pr[i], p0, p1); const LAS float* q = pg + hb * 128 + i * 8; a += dot4(p0, *(const LAS f32x4*)q) + dot4(p1, *(const LAS f32x4*)(q + 4)); }
;         }
;         const float ya = a * FIN(12)[j * 1024 + d] * silu_f(z[1024 + d]);
;         const float vn = vv[k] * rv * FIN(15)[j * 1024 + d];
	v_mul_f32_e32 v5, v5, v17
	v_fmac_f32_e32 v5, v4, v16
	v_mul_f32_e32 v4, v7, v19
	v_fmac_f32_e32 v4, v6, v18
	v_add_f32_e32 v8, v9, v8
	v_add_f32_e32 v4, v5, v4
	v_add_f32_e32 v4, v8, v4
	v_add_f32_e32 v8, v12, v4
	ds_read_b128 v[4:7], v34 offset:480
	v_lshlrev_b32_e32 v9, 16, v0
	v_and_b32_e32 v0, 0xffff0000, v0
	v_lshlrev_b32_e32 v10, 16, v1
	v_and_b32_e32 v11, 0xffff0000, v1
	v_lshlrev_b32_e32 v12, 16, v2
	v_and_b32_e32 v13, 0xffff0000, v2
	v_lshlrev_b32_e32 v14, 16, v3
	v_and_b32_e32 v15, 0xffff0000, v3
	s_waitcnt lgkmcnt(0)
	v_mul_f32_e32 v5, v5, v0
	ds_read_b128 v[0:3], v34 offset:496
	v_fmac_f32_e32 v5, v4, v9
	v_mul_f32_e32 v4, v7, v11
	v_fmac_f32_e32 v4, v6, v10
	v_add_f32_e32 v4, v5, v4
	s_waitcnt lgkmcnt(0)
	v_mul_f32_e32 v1, v1, v13
	v_fmac_f32_e32 v1, v0, v12
	v_mul_f32_e32 v0, v3, v15
	v_fmac_f32_e32 v0, v2, v14
	v_add_f32_e32 v0, v1, v0
	v_add_f32_e32 v0, v4, v0
	v_add_f32_e32 v35, v8, v0
	global_load_dwordx4 v[52:55], v[32:33], off offset:368
	global_load_dwordx4 v[60:63], v[32:33], off offset:352
	global_load_dwordx4 v[64:67], v[32:33], off offset:336
	global_load_dwordx4 v[68:71], v[32:33], off offset:320
	global_load_dwordx4 v[16:19], v[32:33], off offset:432
	global_load_dwordx4 v[72:75], v[32:33], off offset:416
	global_load_dwordx4 v[76:79], v[32:33], off offset:400
	global_load_dwordx4 v[80:83], v[32:33], off offset:384
	global_load_dwordx4 v[0:3], v[32:33], off offset:496
	global_load_dwordx4 v[4:7], v[32:33], off offset:480
	global_load_dwordx4 v[8:11], v[32:33], off offset:464
	global_load_dwordx4 v[12:15], v[32:33], off offset:448
	ds_read_b128 v[84:87], v34 offset:512
	global_load_dword v28, v[28:29], off offset:2048
	s_waitcnt vmcnt(16)
	v_lshlrev_b32_e32 v32, 16, v36
	v_and_b32_e32 v33, 0xffff0000, v36
	v_lshlrev_b32_e32 v56, 16, v37
	v_and_b32_e32 v57, 0xffff0000, v37
	v_lshlrev_b32_e32 v88, 16, v38
	v_and_b32_e32 v89, 0xffff0000, v38
	v_lshlrev_b32_e32 v90, 16, v39
	v_and_b32_e32 v91, 0xffff0000, v39
	ds_read_b128 v[36:39], v34 offset:528
	s_waitcnt lgkmcnt(1)
	v_mul_f32_e32 v33, v85, v33
	v_fmac_f32_e32 v33, v84, v32
	v_mul_f32_e32 v32, v87, v57
	v_fmac_f32_e32 v32, v86, v56
	v_add_f32_e32 v32, v33, v32
	s_waitcnt lgkmcnt(0)
	v_mul_f32_e32 v33, v37, v89
	v_fmac_f32_e32 v33, v36, v88
	v_mul_f32_e32 v36, v39, v91
	v_fmac_f32_e32 v36, v38, v90
	v_add_f32_e32 v33, v33, v36
	ds_read_b128 v[36:39], v34 offset:544
	v_add_f32_e32 v32, v32, v33
	v_add_f32_e32 v32, v35, v32
	s_waitcnt vmcnt(15)
	v_lshlrev_b32_e32 v33, 16, v40
	v_and_b32_e32 v35, 0xffff0000, v40
	v_lshlrev_b32_e32 v56, 16, v41
	v_and_b32_e32 v57, 0xffff0000, v41
	v_lshlrev_b32_e32 v84, 16, v42
	v_and_b32_e32 v85, 0xffff0000, v42
	v_lshlrev_b32_e32 v86, 16, v43
	v_and_b32_e32 v87, 0xffff0000, v43
	ds_read_b128 v[40:43], v34 offset:560
	s_waitcnt lgkmcnt(1)
	v_mul_f32_e32 v35, v37, v35
	v_fmac_f32_e32 v35, v36, v33
	v_mul_f32_e32 v33, v39, v57
	v_fmac_f32_e32 v33, v38, v56
	v_add_f32_e32 v33, v35, v33
	s_waitcnt lgkmcnt(0)
	v_mul_f32_e32 v35, v41, v85
	v_mul_f32_e32 v36, v43, v87
	v_fmac_f32_e32 v35, v40, v84
	v_fmac_f32_e32 v36, v42, v86
	v_add_f32_e32 v35, v35, v36
	ds_read_b128 v[36:39], v34 offset:576
	ds_read_b128 v[40:43], v34 offset:592
	v_add_f32_e32 v33, v33, v35
	s_waitcnt vmcnt(14)
	v_and_b32_e32 v35, 0xffff0000, v44
	v_add_f32_e32 v32, v32, v33
	v_lshlrev_b32_e32 v33, 16, v44
	v_lshlrev_b32_e32 v44, 16, v45
	v_and_b32_e32 v45, 0xffff0000, v45
	s_waitcnt lgkmcnt(1)
	v_mul_f32_e32 v35, v37, v35
	v_fmac_f32_e32 v35, v36, v33
	v_mul_f32_e32 v33, v39, v45
	v_lshlrev_b32_e32 v56, 16, v46
	v_and_b32_e32 v46, 0xffff0000, v46
	v_lshlrev_b32_e32 v57, 16, v47
	v_and_b32_e32 v47, 0xffff0000, v47
	v_fmac_f32_e32 v33, v38, v44
	v_add_f32_e32 v33, v35, v33
	s_waitcnt lgkmcnt(0)
	v_mul_f32_e32 v35, v41, v46
	v_mul_f32_e32 v36, v43, v47
	v_fmac_f32_e32 v35, v40, v56
	v_fmac_f32_e32 v36, v42, v57
	v_add_f32_e32 v35, v35, v36
	ds_read_b128 v[36:39], v34 offset:608
	ds_read_b128 v[40:43], v34 offset:624
	v_add_f32_e32 v33, v33, v35
	s_waitcnt vmcnt(13)
	v_and_b32_e32 v35, 0xffff0000, v48
	v_add_f32_e32 v32, v32, v33
	v_lshlrev_b32_e32 v33, 16, v48
	v_and_b32_e32 v45, 0xffff0000, v49
	s_waitcnt lgkmcnt(1)
	v_mul_f32_e32 v35, v37, v35
	v_lshlrev_b32_e32 v44, 16, v49
	v_fmac_f32_e32 v35, v36, v33
	v_mul_f32_e32 v33, v39, v45
	v_and_b32_e32 v47, 0xffff0000, v50
	v_and_b32_e32 v49, 0xffff0000, v51
	v_fmac_f32_e32 v33, v38, v44
	v_lshlrev_b32_e32 v46, 16, v50
	v_lshlrev_b32_e32 v48, 16, v51
	v_add_f32_e32 v33, v35, v33
	s_waitcnt lgkmcnt(0)
	v_mul_f32_e32 v35, v41, v47
	v_mul_f32_e32 v36, v43, v49
	v_fmac_f32_e32 v35, v40, v46
	v_fmac_f32_e32 v36, v42, v48
	v_add_f32_e32 v35, v35, v36
	ds_read_b128 v[36:39], v34 offset:640
	ds_read_b128 v[40:43], v34 offset:656
	v_add_f32_e32 v33, v33, v35
	s_waitcnt vmcnt(9)
	v_and_b32_e32 v35, 0xffff0000, v68
	v_add_f32_e32 v32, v32, v33
	v_lshlrev_b32_e32 v33, 16, v68
	v_and_b32_e32 v45, 0xffff0000, v69
	s_waitcnt lgkmcnt(1)
	v_mul_f32_e32 v35, v37, v35
	v_lshlrev_b32_e32 v44, 16, v69
	v_fmac_f32_e32 v35, v36, v33
	v_mul_f32_e32 v33, v39, v45
	v_and_b32_e32 v47, 0xffff0000, v70
	v_and_b32_e32 v49, 0xffff0000, v71
	v_fmac_f32_e32 v33, v38, v44
	v_lshlrev_b32_e32 v46, 16, v70
	v_lshlrev_b32_e32 v48, 16, v71
	v_add_f32_e32 v33, v35, v33
	s_waitcnt lgkmcnt(0)
	v_mul_f32_e32 v35, v41, v47
	v_mul_f32_e32 v36, v43, v49
	v_fmac_f32_e32 v35, v40, v46
	v_fmac_f32_e32 v36, v42, v48
	v_add_f32_e32 v35, v35, v36
	ds_read_b128 v[36:39], v34 offset:672
	ds_read_b128 v[40:43], v34 offset:688
	v_add_f32_e32 v33, v33, v35
	v_and_b32_e32 v35, 0xffff0000, v64
	v_add_f32_e32 v32, v32, v33
	v_lshlrev_b32_e32 v33, 16, v64
	v_and_b32_e32 v45, 0xffff0000, v65
	s_waitcnt lgkmcnt(1)
; #define LAS __attribute__((address_space(3)))
; __device__ __forceinline__ float dot4(f32x4 a, f32x4 b) { return (a[0] * b[0] + a[1] * b[1]) + (a[2] * b[2] + a[3] * b[3]); }
; __device__ __forceinline__ void unpack8(u32x4 w, f32x4& a, f32x4& b) { a = (f32x4){bflo(w.x), bfhi(w.x), bflo(w.y), bfhi(w.y)}; b = (f32x4){bflo(w.z), bfhi(w.z), bflo(w.w), bfhi(w.w)}; }
; __device__ __forceinline__ void sample_mix_even(Frame& F0, int j, int b) {
;     ...
; #pragma unroll
;         for (int hb = 0; hb < 2; ++hb) {
;             u32x4 pr[16];
; #pragma unroll
;             for (int i = 0; i < 16; ++i) pr[i] = *(const u32x4*)(pm + hb * 128 + i * 8);
; #pragma unroll
;             for (int i = 0; i < 16; ++i) { f32x4 p0, p1; unpack8(pr[i], p0, p1); const LAS float* q = pg + hb * 128 + i * 8; a += dot4(p0, *(const LAS f32x4*)q) + dot4(p1, *(const LAS f32x4*)(q + 4)); }
	v_mul_f32_e32 v35, v37, v35
	v_lshlrev_b32_e32 v44, 16, v65
	v_fmac_f32_e32 v35, v36, v33
	v_mul_f32_e32 v33, v39, v45
	v_and_b32_e32 v47, 0xffff0000, v66
	v_and_b32_e32 v49, 0xffff0000, v67
	v_fmac_f32_e32 v33, v38, v44
	v_lshlrev_b32_e32 v46, 16, v66
	v_lshlrev_b32_e32 v48, 16, v67
	v_add_f32_e32 v33, v35, v33
	s_waitcnt lgkmcnt(0)
	v_mul_f32_e32 v35, v41, v47
	v_mul_f32_e32 v36, v43, v49
	v_fmac_f32_e32 v35, v40, v46
	v_fmac_f32_e32 v36, v42, v48
	v_add_f32_e32 v35, v35, v36
	ds_read_b128 v[36:39], v34 offset:704
	ds_read_b128 v[40:43], v34 offset:720
	v_add_f32_e32 v33, v33, v35
	v_and_b32_e32 v35, 0xffff0000, v60
	v_add_f32_e32 v32, v32, v33
	v_lshlrev_b32_e32 v33, 16, v60
	v_and_b32_e32 v45, 0xffff0000, v61
	s_waitcnt lgkmcnt(1)
	v_mul_f32_e32 v35, v37, v35
	v_lshlrev_b32_e32 v44, 16, v61
	v_fmac_f32_e32 v35, v36, v33
	v_mul_f32_e32 v33, v39, v45
	v_and_b32_e32 v47, 0xffff0000, v62
	v_and_b32_e32 v49, 0xffff0000, v63
	v_fmac_f32_e32 v33, v38, v44
	v_lshlrev_b32_e32 v46, 16, v62
	v_lshlrev_b32_e32 v48, 16, v63
	v_add_f32_e32 v33, v35, v33
	s_waitcnt lgkmcnt(0)
	v_mul_f32_e32 v35, v41, v47
	v_mul_f32_e32 v36, v43, v49
	v_fmac_f32_e32 v35, v40, v46
	v_fmac_f32_e32 v36, v42, v48
	v_add_f32_e32 v35, v35, v36
	ds_read_b128 v[36:39], v34 offset:736
	ds_read_b128 v[40:43], v34 offset:752
	v_add_f32_e32 v33, v33, v35
	v_and_b32_e32 v35, 0xffff0000, v52
	v_add_f32_e32 v32, v32, v33
	v_lshlrev_b32_e32 v33, 16, v52
	v_and_b32_e32 v45, 0xffff0000, v53
	s_waitcnt lgkmcnt(1)
	v_mul_f32_e32 v35, v37, v35
	v_lshlrev_b32_e32 v44, 16, v53
	v_fmac_f32_e32 v35, v36, v33
	v_mul_f32_e32 v33, v39, v45
	v_and_b32_e32 v47, 0xffff0000, v54
	v_and_b32_e32 v49, 0xffff0000, v55
	v_fmac_f32_e32 v33, v38, v44
	v_lshlrev_b32_e32 v46, 16, v54
	v_lshlrev_b32_e32 v48, 16, v55
	v_add_f32_e32 v33, v35, v33
	s_waitcnt lgkmcnt(0)
	v_mul_f32_e32 v35, v41, v47
	v_mul_f32_e32 v36, v43, v49
	v_fmac_f32_e32 v35, v40, v46
	v_fmac_f32_e32 v36, v42, v48
	v_add_f32_e32 v35, v35, v36
	ds_read_b128 v[36:39], v34 offset:768
	ds_read_b128 v[40:43], v34 offset:784
	v_add_f32_e32 v33, v33, v35
	s_waitcnt vmcnt(5)
	v_and_b32_e32 v35, 0xffff0000, v80
	v_add_f32_e32 v32, v32, v33
	v_lshlrev_b32_e32 v33, 16, v80
	v_and_b32_e32 v45, 0xffff0000, v81
	s_waitcnt lgkmcnt(1)
	v_mul_f32_e32 v35, v37, v35
	v_lshlrev_b32_e32 v44, 16, v81
	v_fmac_f32_e32 v35, v36, v33
	v_mul_f32_e32 v33, v39, v45
	v_and_b32_e32 v47, 0xffff0000, v82
	v_and_b32_e32 v49, 0xffff0000, v83
	v_fmac_f32_e32 v33, v38, v44
	v_lshlrev_b32_e32 v46, 16, v82
	v_lshlrev_b32_e32 v48, 16, v83
	v_add_f32_e32 v33, v35, v33
	s_waitcnt lgkmcnt(0)
	v_mul_f32_e32 v35, v41, v47
	v_mul_f32_e32 v36, v43, v49
	v_fmac_f32_e32 v35, v40, v46
	v_fmac_f32_e32 v36, v42, v48
	v_add_f32_e32 v35, v35, v36
	ds_read_b128 v[36:39], v34 offset:800
	ds_read_b128 v[40:43], v34 offset:816
	v_add_f32_e32 v33, v33, v35
	v_and_b32_e32 v35, 0xffff0000, v76
	v_add_f32_e32 v32, v32, v33
	v_lshlrev_b32_e32 v33, 16, v76
	v_and_b32_e32 v45, 0xffff0000, v77
	s_waitcnt lgkmcnt(1)
	v_mul_f32_e32 v35, v37, v35
	v_lshlrev_b32_e32 v44, 16, v77
	v_fmac_f32_e32 v35, v36, v33
	v_mul_f32_e32 v33, v39, v45
	v_and_b32_e32 v47, 0xffff0000, v78
	v_and_b32_e32 v49, 0xffff0000, v79
	v_fmac_f32_e32 v33, v38, v44
	ds_read_b128 v[36:39], v34 offset:832
	v_lshlrev_b32_e32 v46, 16, v78
	v_lshlrev_b32_e32 v48, 16, v79
	v_add_f32_e32 v29, v35, v33
	s_waitcnt lgkmcnt(1)
	v_mul_f32_e32 v33, v41, v47
	v_mul_f32_e32 v35, v43, v49
	v_fmac_f32_e32 v33, v40, v46
	v_fmac_f32_e32 v35, v42, v48
	v_add_f32_e32 v33, v33, v35
	ds_read_b128 v[40:43], v34 offset:848
	v_add_f32_e32 v29, v29, v33
	v_and_b32_e32 v33, 0xffff0000, v72
	v_add_f32_e32 v29, v32, v29
	v_lshlrev_b32_e32 v32, 16, v72
	v_and_b32_e32 v44, 0xffff0000, v73
	s_waitcnt lgkmcnt(1)
	v_mul_f32_e32 v33, v37, v33
	v_lshlrev_b32_e32 v35, 16, v73
	v_fmac_f32_e32 v33, v36, v32
	v_mul_f32_e32 v32, v39, v44
	v_and_b32_e32 v46, 0xffff0000, v74
	v_and_b32_e32 v48, 0xffff0000, v75
	v_fmac_f32_e32 v32, v38, v35
	v_lshlrev_b32_e32 v45, 16, v74
	v_lshlrev_b32_e32 v47, 16, v75
	v_add_f32_e32 v32, v33, v32
	s_waitcnt lgkmcnt(0)
	v_mul_f32_e32 v33, v41, v46
	v_mul_f32_e32 v35, v43, v48
	ds_read_b128 v[36:39], v34 offset:864
	v_fmac_f32_e32 v33, v40, v45
	v_fmac_f32_e32 v35, v42, v47
	v_add_f32_e32 v33, v33, v35
	v_add_f32_e32 v32, v32, v33
	v_add_f32_e32 v29, v29, v32
	v_lshlrev_b32_e32 v32, 16, v16
	v_and_b32_e32 v16, 0xffff0000, v16
	v_lshlrev_b32_e32 v33, 16, v17
	v_and_b32_e32 v35, 0xffff0000, v17
	v_lshlrev_b32_e32 v40, 16, v18
	v_and_b32_e32 v41, 0xffff0000, v18
	v_lshlrev_b32_e32 v42, 16, v19
	v_and_b32_e32 v43, 0xffff0000, v19
	s_waitcnt lgkmcnt(0)
; __device__ __forceinline__ unsigned cvt_pk_bf16(float lo, float hi) { const f32x2cv v = {lo, hi}; return __builtin_bit_cast(unsigned, __builtin_convertvector(v, bf16x2cv)); }
; #define LAS __attribute__((address_space(3)))
; __device__ __forceinline__ float silu_f(float x) { return x * __builtin_amdgcn_rcpf(1.f + __builtin_amdgcn_exp2f(-1.4426950408889634f * x)); }
; __device__ __forceinline__ float dot4(f32x4 a, f32x4 b) { return (a[0] * b[0] + a[1] * b[1]) + (a[2] * b[2] + a[3] * b[3]); }
; __device__ __forceinline__ void unpack8(u32x4 w, f32x4& a, f32x4& b) { a = (f32x4){bflo(w.x), bfhi(w.x), bflo(w.y), bfhi(w.y)}; b = (f32x4){bflo(w.z), bfhi(w.z), bflo(w.w), bfhi(w.w)}; }
; __device__ __forceinline__ void sample_mix_even(Frame& F0, int j, int b) {
;     ...
;             for (int i = 0; i < 16; ++i) pr[i] = *(const u32x4*)(pm + hb * 128 + i * 8);
; #pragma unroll
;             for (int i = 0; i < 16; ++i) { f32x4 p0, p1; unpack8(pr[i], p0, p1); const LAS float* q = pg + hb * 128 + i * 8; a += dot4(p0, *(const LAS f32x4*)q) + dot4(p1, *(const LAS f32x4*)(q + 4)); }
;         }
;         const float ya = a * FIN(12)[j * 1024 + d] * silu_f(z[1024 + d]);
;         const float vn = vv[k] * rv * FIN(15)[j * 1024 + d];
;         F.out[O_SGUV + (size_t)(j * 128 + b) * 1024 + d] = vn;
;         const float mixed = FIN(13)[(size_t)(j * 4 + g) * 16384] * vn + FIN(14)[(j * 4 + g) * 128];
;         const float yb = z[2048 + d] * mixed * silu_f(z[4096 + d]);
;         ((bf16_t*)(F.ws + WS_SA2))[(size_t)b * 2048 + d] = (bf16_t)(cvt_pk_bf16(ya, 0.f) & 0xffffu); ((bf16_t*)(F.ws + WS_SA2))[(size_t)b * 2048 + 1024 + d] = (bf16_t)(cvt_pk_bf16(yb, 0.f) & 0xffffu);
;     }
;     __syncthreads();
	v_mul_f32_e32 v37, v37, v16
	ds_read_b128 v[16:19], v34 offset:880
	v_fmac_f32_e32 v37, v36, v32
	v_mul_f32_e32 v32, v39, v35
	v_fmac_f32_e32 v32, v38, v33
	v_add_f32_e32 v32, v37, v32
	s_waitcnt lgkmcnt(0)
	v_mul_f32_e32 v17, v17, v41
	ds_read_b128 v[36:39], v34 offset:896
	v_fmac_f32_e32 v17, v16, v40
	v_mul_f32_e32 v16, v19, v43
	v_fmac_f32_e32 v16, v18, v42
	ds_read_b128 v[40:43], v34 offset:912
	v_add_f32_e32 v16, v17, v16
	s_waitcnt vmcnt(1)
	v_lshlrev_b32_e32 v17, 16, v12
	v_and_b32_e32 v12, 0xffff0000, v12
	v_lshlrev_b32_e32 v18, 16, v13
	v_and_b32_e32 v13, 0xffff0000, v13
	s_waitcnt lgkmcnt(1)
	v_mul_f32_e32 v12, v37, v12
	v_mul_f32_e32 v13, v39, v13
	v_add_f32_e32 v16, v32, v16
	v_lshlrev_b32_e32 v19, 16, v14
	v_and_b32_e32 v14, 0xffff0000, v14
	v_and_b32_e32 v32, 0xffff0000, v15
	v_fmac_f32_e32 v12, v36, v17
	v_fmac_f32_e32 v13, v38, v18
	v_add_f32_e32 v16, v29, v16
	v_lshlrev_b32_e32 v29, 16, v15
	v_add_f32_e32 v15, v12, v13
	s_waitcnt lgkmcnt(0)
	v_mul_f32_e32 v12, v41, v14
	v_mul_f32_e32 v13, v43, v32
	v_fmac_f32_e32 v12, v40, v19
	v_fmac_f32_e32 v13, v42, v29
	v_add_f32_e32 v17, v12, v13
	v_add_co_u32_e32 v12, vcc, s70, v24
	v_mul_f32_e32 v19, v58, v59
	s_nop 0
	v_addc_co_u32_e32 v13, vcc, 0, v25, vcc
	s_waitcnt vmcnt(0)
	v_mul_f32_e32 v19, v19, v28
	v_add_co_u32_e32 v24, vcc, s94, v24
	global_load_dword v14, v[30:31], off offset:2048
	global_load_dword v18, v[12:13], off offset:-4096
	v_addc_co_u32_e32 v25, vcc, 0, v25, vcc
	global_store_dword v[26:27], v19, off offset:2048
	global_load_dword v26, v[24:25], off
	v_lshlrev_b64 v[24:25], 16, v[22:23]
	v_lshlrev_b32_e32 v22, 7, v22
	v_lshl_add_u64 v[24:25], s[6:7], 0, v[24:25]
	v_ashrrev_i32_e32 v23, 31, v22
	v_add_f32_e32 v15, v15, v17
	global_load_dword v17, v[24:25], off
	v_lshl_add_u64 v[22:23], v[22:23], 2, s[8:9]
	global_load_dword v27, v[22:23], off
	s_nop 0
	global_load_dword v12, v[12:13], off
	ds_read_b128 v[22:25], v34 offset:928
	v_add_f32_e32 v13, v16, v15
	v_lshlrev_b32_e32 v15, 16, v8
	v_and_b32_e32 v8, 0xffff0000, v8
	v_lshlrev_b32_e32 v16, 16, v9
	v_and_b32_e32 v28, 0xffff0000, v9
	v_lshlrev_b32_e32 v29, 16, v10
	v_and_b32_e32 v30, 0xffff0000, v10
	v_lshlrev_b32_e32 v31, 16, v11
	v_and_b32_e32 v32, 0xffff0000, v11
	s_waitcnt lgkmcnt(0)
	v_mul_f32_e32 v23, v23, v8
	ds_read_b128 v[8:11], v34 offset:944
	v_fmac_f32_e32 v23, v22, v15
	v_mul_f32_e32 v15, v25, v28
	v_fmac_f32_e32 v15, v24, v16
	v_add_f32_e32 v15, v23, v15
	s_waitcnt lgkmcnt(0)
	v_mul_f32_e32 v9, v9, v30
	v_fmac_f32_e32 v9, v8, v29
	v_mul_f32_e32 v8, v11, v32
	v_fmac_f32_e32 v8, v10, v31
	v_add_f32_e32 v8, v9, v8
	v_add_f32_e32 v8, v15, v8
	v_add_f32_e32 v13, v13, v8
	ds_read_b128 v[8:11], v34 offset:960
	v_lshlrev_b32_e32 v15, 16, v4
	v_and_b32_e32 v4, 0xffff0000, v4
	v_lshlrev_b32_e32 v16, 16, v5
	v_and_b32_e32 v22, 0xffff0000, v5
	v_lshlrev_b32_e32 v23, 16, v6
	v_and_b32_e32 v24, 0xffff0000, v6
	v_lshlrev_b32_e32 v25, 16, v7
	v_and_b32_e32 v28, 0xffff0000, v7
	s_waitcnt lgkmcnt(0)
	v_mul_f32_e32 v9, v9, v4
	ds_read_b128 v[4:7], v34 offset:976
	v_fmac_f32_e32 v9, v8, v15
	v_mul_f32_e32 v8, v11, v22
	v_fmac_f32_e32 v8, v10, v16
	v_add_f32_e32 v8, v9, v8
	s_waitcnt lgkmcnt(0)
	v_mul_f32_e32 v5, v5, v24
	v_fmac_f32_e32 v5, v4, v23
	v_mul_f32_e32 v4, v7, v28
	v_fmac_f32_e32 v4, v6, v25
	v_add_f32_e32 v4, v5, v4
	v_add_f32_e32 v4, v8, v4
	v_add_f32_e32 v8, v13, v4
	ds_read_b128 v[4:7], v34 offset:992
	v_lshlrev_b32_e32 v9, 16, v0
	v_and_b32_e32 v0, 0xffff0000, v0
	v_lshlrev_b32_e32 v10, 16, v1
	v_and_b32_e32 v11, 0xffff0000, v1
	v_lshlrev_b32_e32 v13, 16, v2
	v_and_b32_e32 v15, 0xffff0000, v2
	v_lshlrev_b32_e32 v16, 16, v3
	v_and_b32_e32 v22, 0xffff0000, v3
	s_waitcnt lgkmcnt(0)
	v_mul_f32_e32 v5, v5, v0
	ds_read_b128 v[0:3], v34 offset:1008
	v_fmac_f32_e32 v5, v4, v9
	v_mul_f32_e32 v4, v7, v11
	v_fmac_f32_e32 v4, v6, v10
	v_add_f32_e32 v4, v5, v4
	s_waitcnt lgkmcnt(0)
	v_mul_f32_e32 v1, v1, v15
	v_fmac_f32_e32 v1, v0, v13
	v_mul_f32_e32 v0, v3, v22
	v_fmac_f32_e32 v0, v2, v16
	v_add_f32_e32 v0, v1, v0
	v_add_f32_e32 v0, v4, v0
	v_add_f32_e32 v0, v8, v0
	s_waitcnt vmcnt(5)
	v_mul_f32_e32 v3, 0xbfb8aa3b, v18
	v_exp_f32_e32 v3, v3
	v_mul_f32_e32 v0, v14, v0
	s_waitcnt vmcnt(3)
	v_mul_f32_e32 v2, 0xbfb8aa3b, v26
	v_exp_f32_e32 v2, v2
	v_add_f32_e32 v1, 1.0, v3
	v_rcp_f32_e32 v1, v1
	v_add_f32_e32 v2, 1.0, v2
	v_rcp_f32_e32 v2, v2
	v_mul_f32_e32 v1, v18, v1
	s_waitcnt vmcnt(1)
	v_fmac_f32_e32 v27, v19, v17
	v_mul_f32_e32 v0, v0, v1
	s_waitcnt vmcnt(0)
	v_mul_f32_e32 v1, v12, v27
	v_mul_f32_e32 v2, v26, v2
	v_mul_f32_e32 v1, v1, v2
	v_cvt_pk_bf16_f32 v0, v0, s0
	global_store_short v[20:21], v0, off offset:1024
	v_cvt_pk_bf16_f32 v0, v1, s0
	global_store_short v[20:21], v0, off offset:3072
.Lsmx_end:
	s_barrier
	s_cbranch_scc0 .LBB0_1609
